# attention loop unrolled 2x with immediate ring-slot offsets (no per-tile address VALU), fp8 ones operand kept resident, QK segment priority raise, counted lgkmcnt waits
# speedup vs baseline: 1.0323x; 1.0323x over previous
; #define LAS __attribute__((address_space(3)))
; __device__ __forceinline__ int lane_id() { return (int)__builtin_amdgcn_mbcnt_hi(~0u, __builtin_amdgcn_mbcnt_lo(~0u, 0u)); }
; #define lane lane_id()
; __device__ __forceinline__ void body(const unsigned char* Q8b, const unsigned char* K8h, const unsigned char* VT8h, const bf16_t* Gb, bf16_t* Ob, int seq, char* lds, const int wid, ...
;   const int lane = lane_id(), tid = wid * 64 + lane, r32 = lane & 31, hi = lane >> 5;
;   char* V_lds = lds; char* K_lds = lds + K_OFF;
;   float* ws = (float*)(lds + WS_OFF) + wid * 64; float* al_l = ws + 32;
;   f32x16 o[4] = {}; f32x16 ls = {}; f32x16 nm;
; #pragma unroll
;   for (int r = 0; r < 16; ++r) nm[r] = PSHIFT;
;   LAS char* L3 = (LAS char*)lds;
;   const int krow = wid * 8 + (lane >> 3), kc = (lane & 7) ^ ((krow >> 1) & 7);
;   const char* Kg = (const char*)K8h + krow * 256 + kc * 16; const char* Vg = (const char*)VT8h + wid * 1024 + lane * 16;
;   const int ksw = (r32 >> 1) & 7, ko = r32 * 128, c00 = ((0 + hi * 2) ^ ksw) << 4, c01 = ((1 + hi * 2) ^ ksw) << 4, c10 = ((4 + hi * 2) ^ ksw) << 4, c11 = ((5 + hi * 2) ^ ksw) << 4;
;   const int vsw = (r32 >> 2) & 3, vo = r32 * 64, e0 = ((2 * hi) ^ vsw) << 4, e1 = ((2 * hi + 1) ^ vsw) << 4;
;     ...
;   for (int r = 0; r < 16; ++r) rli[r] = __builtin_amdgcn_rcpf(ls[r]);
;   const int rw = lane >> 4, ch = lane & 15;
;   const bf16_t* Gw = Gb + (wid * QBLK + rw) * LDO + ch * 8; bf16_t* Ow = Ob + (wid * QBLK + rw) * LDO + ch * 8;
;   u32x4 gv[8];
; #pragma unroll
;   for (int i = 0; i < 8; ++i) gv[i] = *(const u32x4*)(Gw + i * 4 * LDO);
.LBB0_357:
	s_and_b64 vcc, exec, s[4:5]
	s_cbranch_vccnz .LBB0_393
	v_mbcnt_lo_u32_b32 v0, -1, 0
	v_mbcnt_hi_u32_b32 v1, -1, v0
	s_and_b32 s4, s2, 7
	v_lshrrev_b32_e32 v9, 5, v1
	s_mul_i32 s4, s4, 10
	v_bfe_u32 v5, v1, 1, 3
	v_lshlrev_b32_e32 v6, 1, v9
	s_or_b32 s29, s4, 1
	s_ashr_i32 s31, s2, 3
	v_bitop3_b32 v5, v6, v5, 1 bitop3:0x36
	s_waitcnt lgkmcnt(0)
	s_add_u32 s63, s8, 0xc000000
	v_lshrrev_b32_e32 v4, 1, v1
	v_lshlrev_b32_e32 v229, 4, v5
	v_add_u32_e32 v5, 4, v6
	s_addc_u32 s64, s9, 0
	v_lshrrev_b32_e32 v0, 3, v1
	v_bitop3_b32 v5, v5, v4, 7 bitop3:0x78
	s_add_u32 s65, s8, 0x16000000
	v_lshl_add_u32 v0, s33, 3, v0
	v_lshlrev_b32_e32 v230, 4, v5
	v_add_u32_e32 v5, 5, v6
	s_addc_u32 s66, s9, 0
	s_lshl_b32 s4, s33, 8
	v_lshrrev_b32_e32 v2, 1, v0
	v_bitop3_b32 v7, v6, v4, 7 bitop3:0x78
	v_bitop3_b32 v4, v5, v4, 7 bitop3:0x78
	s_add_i32 s67, s4, 0
	v_xor_b32_e32 v2, v2, v1
	v_lshlrev_b32_e32 v231, 4, v4
	v_lshrrev_b32_e32 v4, 2, v1
	s_add_i32 s67, s67, 0x10000
	v_lshlrev_b32_e32 v202, 8, v0
	v_lshlrev_b32_e32 v0, 4, v2
	s_lshl_b32 s10, s33, 10
	v_bfe_u32 v5, v1, 2, 2
	v_bitop3_b32 v4, v6, v4, 3 bitop3:0x78
	v_and_b32_e32 v8, 31, v1
	v_and_b32_e32 v204, 0x70, v0
	v_mov_b32_e32 v0, 0
	s_add_u32 s4, s8, s10
	v_lshlrev_b32_e32 v232, 4, v4
	v_bitop3_b32 v4, v6, v5, 1 bitop3:0x36
	v_lshlrev_b32_e32 v2, 4, v1
	v_mov_b32_e32 v3, v0
	s_addc_u32 s5, s9, 0
	v_lshlrev_b32_e32 v233, 4, v4
	s_add_i32 s68, s10, 0
	v_lshl_add_u32 v234, v8, 7, 0
	v_lshlrev_b32_e32 v4, 6, v8
	s_lshl_b32 s10, s33, 15
	v_lshrrev_b32_e32 v10, 4, v1
	v_lshl_add_u64 v[2:3], s[4:5], 0, v[2:3]
	s_mov_b64 s[4:5], 0x18800000
	v_sub_u32_e32 v235, v234, v4
	v_lshl_or_b32 v4, v10, 10, s10
	v_lshl_add_u64 v[206:207], v[2:3], 0, s[4:5]
	v_cmp_gt_u32_e64 s[4:5], 32, v1
	v_and_b32_e32 v210, 0x60, v1
	v_and_b32_e32 v1, 15, v1
	v_ashrrev_i32_e32 v5, 31, v4
	v_lshlrev_b32_e32 v228, 4, v7
	v_lshlrev_b32_e32 v6, 4, v1
	v_mov_b32_e32 v7, v0
	v_lshl_add_u64 v[4:5], v[4:5], 1, s[8:9]
	v_lshl_or_b32 v208, v8, 10, s10
	v_lshl_add_u64 v[4:5], v[4:5], 0, v[6:7]
	s_mov_b64 s[10:11], 0x1b000000
	v_lshl_add_u64 v[212:213], v[4:5], 0, s[10:11]
	s_mul_i32 s10, s33, 0x2200
	s_add_i32 s10, s10, 0
	s_add_i32 s12, s10, 0x10800
	v_lshlrev_b32_e32 v1, 1, v8
	v_mul_u32_u24_e32 v7, 0x440, v9
	s_mov_b64 s[10:11], 0x2000000
	v_add3_u32 v238, s12, v1, v7
	v_lshl_add_u64 v[214:215], v[4:5], 0, s[10:11]
	s_movk_i32 s10, 0x110
	v_mov_b32_e32 v1, s12
	v_ashrrev_i32_e32 v203, 31, v202
	v_mad_u32_u24 v1, v10, s10, v1
	s_mov_b64 s[10:11], 0x18806000
	v_lshl_add_u64 v[216:217], v[2:3], 0, s[10:11]
	v_or_b32_e32 v2, v202, v204
	v_mov_b32_e32 v3, v203
	v_lshl_add_u64 v[2:3], s[8:9], 0, v[2:3]
	s_mov_b64 s[8:9], 0x1600c000
	v_lshl_add_u64 v[218:219], v[2:3], 0, s[8:9]
	s_mov_b32 s8, 0x40a00000
	s_mov_b32 s37, 0
	v_mov_b32_e32 v205, v0
	v_lshl_add_u32 v236, v8, 2, s67
	v_lshlrev_b32_e32 v237, 4, v9
	v_ashrrev_i32_e32 v209, 31, v208
	v_mov_b32_e32 v211, v0
	s_mov_b32 s69, 0x8000
	s_add_i32 s70, s68, 0x8000
	s_mov_b64 s[38:39], 0x4000
	s_mov_b32 s71, 0xa000
	s_add_i32 s72, s68, 0xa000
	s_mov_b64 s[40:41], 0x2000
	s_movk_i32 s73, 0x2000
	s_add_i32 s74, s68, 0x2000
	s_mov_b64 s[42:43], 0x8000
	s_mov_b32 s75, 0xc000
	s_add_i32 s76, s68, 0xc000
	s_movk_i32 s77, 0x4000
	s_add_i32 s78, s68, 0x4000
	s_mov_b32 s9, s8
	s_mov_b32 s10, s8
	s_mov_b32 s11, s8
	s_mov_b32 s12, s8
	s_mov_b32 s13, s8
	s_mov_b32 s14, s8
	s_mov_b32 s15, s8
	s_mov_b32 s16, s8
	s_mov_b32 s17, s8
	s_mov_b32 s18, s8
	s_mov_b32 s19, s8
	s_mov_b32 s20, s8
	s_mov_b32 s21, s8
	s_mov_b32 s22, s8
	s_mov_b32 s23, s8
	v_mov_b32_e32 v239, 0x7c7c7c7c
	v_mov_b32_e32 v240, 0x7f7f7f7f
	s_movk_i32 s79, 0x6000
	s_mov_b32 s80, 0x40fc551e
	s_mov_b32 s81, 0xe000
	v_add_u32_e32 v241, v1, v6
	v_mov_b32_e32 v192, 0x38383838
	s_mov_b32 s82, 0
	s_lshr_b32 s92, s33, 2
	v_add_u32_e32 v242, v234, v228
	v_add_u32_e32 v243, v234, v229
	v_add_u32_e32 v244, v234, v230
	v_add_u32_e32 v245, v234, v231
	v_add_u32_e32 v254, v235, v232
	v_add_u32_e32 v255, v235, v233
	v_mov_b32_e32 v228, v192
	v_mov_b32_e32 v229, v192
	v_mov_b32_e32 v230, v192
	v_mov_b32_e32 v231, v192
	v_mov_b32_e32 v232, v192
	v_mov_b32_e32 v233, v192
	v_mov_b32_e32 v234, v192
	v_mov_b32_e32 v235, v192
	s_mov_b32 s93, 0
	s_branch .LBB0_360
.LBB0_359:
	s_ashr_i32 s53, s52, 31
	s_lshl_b64 s[52:53], s[52:53], 18
	v_mfma_scale_f32_32x32x64_f8f6f4 v[80:95], v[96:103], v[228:235], v[80:95], v240, v240 op_sel_hi:[0,0,0]
	s_lshl_b64 s[50:51], s[50:51], 23
	s_lshl_b32 s36, s84, 7
	s_add_u32 s36, s52, s36
	s_addc_u32 s45, s53, 0
	s_add_u32 s50, s36, s50
	s_addc_u32 s51, s45, s51
	s_lshl_b64 s[50:51], s[50:51], 1
	v_lshl_add_u64 v[10:11], v[212:213], 0, s[50:51]
	v_add_co_u32_e32 v12, vcc, s73, v10
	s_add_i32 s82, s82, 1
	s_nop 0
	v_addc_co_u32_e32 v13, vcc, 0, v11, vcc
	global_load_dwordx4 v[112:115], v[10:11], off
	global_load_dwordx4 v[108:111], v[12:13], off
	v_add_co_u32_e32 v12, vcc, s77, v10
	s_waitcnt lgkmcnt(0)
; __device__ __forceinline__ unsigned cvt_pk_bf16(float lo, float hi) { unsigned r; asm volatile("v_cvt_pk_bf16_f32 %0, %1, %2" : "=v"(r) : "v"(lo), "v"(hi)); return r; }
; #define lane lane_id()
; __device__ __forceinline__ void body(const unsigned char* Q8b, const unsigned char* K8h, const unsigned char* VT8h, const bf16_t* Gb, bf16_t* Ob, int seq, char* lds, const int wid, ...
;     ...
;   float rli[16];
; #pragma unroll
;   for (int r = 0; r < 16; ++r) rli[r] = __builtin_amdgcn_rcpf(ls[r]);
;   const int rw = lane >> 4, ch = lane & 15;
;   const bf16_t* Gw = Gb + (wid * QBLK + rw) * LDO + ch * 8; bf16_t* Ow = Ob + (wid * QBLK + rw) * LDO + ch * 8;
;   u32x4 gv[8];
; #pragma unroll
;   for (int i = 0; i < 8; ++i) gv[i] = *(const u32x4*)(Gw + i * 4 * LDO);
;   char* st = lds + ST_OFF + wid * (QBLK * ST_ROW) + r32 * 2 + hi * 4 * ST_ROW;
; #pragma unroll
;   for (int r = 0; r < 16; ++r) {
; #pragma unroll
;     for (int d0 = 0; d0 < 4; ++d0) *(bf16_t*)(st + ((r & 3) + 8 * (r >> 2)) * ST_ROW + d0 * 64) = (bf16_t)cvt_pk_bf16(o[d0][r] * rli[r], 0.f); }
	v_mfma_scale_f32_32x32x64_f8f6f4 v[64:79], v[96:103], v[144:151], v[64:79], v240, v240 op_sel_hi:[0,0,0]
	v_addc_co_u32_e32 v13, vcc, 0, v11, vcc
	v_add_co_u32_e32 v14, vcc, s79, v10
	v_rcp_f32_e32 v127, v92
	s_nop 0
	v_addc_co_u32_e32 v15, vcc, 0, v11, vcc
	v_rcp_f32_e32 v144, v93
	v_rcp_f32_e32 v145, v94
	v_rcp_f32_e32 v146, v95
	global_load_dwordx4 v[104:107], v[12:13], off
	global_load_dwordx4 v[92:95], v[14:15], off
	v_add_co_u32_e32 v12, vcc, s69, v10
	v_rcp_f32_e32 v1, v80
	s_nop 0
	v_addc_co_u32_e32 v13, vcc, 0, v11, vcc
	v_mfma_scale_f32_32x32x64_f8f6f4 v[48:63], v[96:103], v[136:143], v[48:63], v240, v240 op_sel_hi:[0,0,0]
	v_add_co_u32_e32 v14, vcc, s71, v10
	v_rcp_f32_e32 v119, v84
	s_nop 0
	v_addc_co_u32_e32 v15, vcc, 0, v11, vcc
	v_rcp_f32_e32 v120, v85
	v_rcp_f32_e32 v121, v86
	v_rcp_f32_e32 v122, v87
	v_rcp_f32_e32 v123, v88
	v_rcp_f32_e32 v124, v89
	v_rcp_f32_e32 v125, v90
	v_rcp_f32_e32 v126, v91
	global_load_dwordx4 v[88:91], v[12:13], off
	global_load_dwordx4 v[84:87], v[14:15], off
	v_add_co_u32_e32 v12, vcc, s75, v10
	v_mfma_scale_f32_32x32x64_f8f6f4 v[32:47], v[96:103], v[128:135], v[32:47], v240, v240 op_sel_hi:[0,0,0]
	s_nop 0
	v_addc_co_u32_e32 v13, vcc, 0, v11, vcc
	v_add_co_u32_e32 v10, vcc, s81, v10
	v_rcp_f32_e32 v116, v81
	s_nop 0
	v_addc_co_u32_e32 v11, vcc, 0, v11, vcc
	v_mul_f32_e32 v14, v64, v1
	v_rcp_f32_e32 v117, v82
	v_rcp_f32_e32 v118, v83
	global_load_dwordx4 v[80:83], v[12:13], off
	s_nop 0
	global_load_dwordx4 v[10:13], v[10:11], off
	v_cvt_pk_bf16_f32 v14, v14, v0
	ds_write_b16 v238, v14
	v_mul_f32_e32 v14, v48, v1
	v_cvt_pk_bf16_f32 v14, v14, v0
	v_mfma_scale_f32_32x32x64_f8f6f4 v[16:31], v[96:103], v[2:9], v[16:31], v240, v240 op_sel_hi:[0,0,0]
	s_nop 4
	v_mul_f32_e32 v2, v32, v1
	ds_write_b16 v238, v14 offset:64
	v_cvt_pk_bf16_f32 v2, v2, v0
	ds_write_b16 v238, v2 offset:128
	v_lshl_add_u64 v[2:3], v[214:215], 0, s[50:51]
	s_mov_b32 s50, s44
	s_mov_b32 s84, s83
	s_mov_b32 s52, s46
	s_nop 7
	v_mul_f32_e32 v1, v16, v1
	v_cvt_pk_bf16_f32 v1, v1, v0
	ds_write_b16 v238, v1 offset:192
	v_mul_f32_e32 v1, v65, v116
	v_cvt_pk_bf16_f32 v1, v1, v0
	ds_write_b16 v238, v1 offset:272
	v_mul_f32_e32 v1, v49, v116
	v_cvt_pk_bf16_f32 v1, v1, v0
	ds_write_b16 v238, v1 offset:336
	v_mul_f32_e32 v1, v33, v116
	v_cvt_pk_bf16_f32 v1, v1, v0
	ds_write_b16 v238, v1 offset:400
	v_mul_f32_e32 v1, v17, v116
	v_cvt_pk_bf16_f32 v1, v1, v0
	ds_write_b16 v238, v1 offset:464
	v_mul_f32_e32 v1, v66, v117
	v_cvt_pk_bf16_f32 v1, v1, v0
	ds_write_b16 v238, v1 offset:544
	v_mul_f32_e32 v1, v50, v117
	v_cvt_pk_bf16_f32 v1, v1, v0
	ds_write_b16 v238, v1 offset:608
	v_mul_f32_e32 v1, v34, v117
	v_cvt_pk_bf16_f32 v1, v1, v0
	ds_write_b16 v238, v1 offset:672
	v_mul_f32_e32 v1, v18, v117
	v_cvt_pk_bf16_f32 v1, v1, v0
	ds_write_b16 v238, v1 offset:736
	v_mul_f32_e32 v1, v67, v118
	v_cvt_pk_bf16_f32 v1, v1, v0
	ds_write_b16 v238, v1 offset:816
	v_mul_f32_e32 v1, v51, v118
	v_cvt_pk_bf16_f32 v1, v1, v0
	ds_write_b16 v238, v1 offset:880
	v_mul_f32_e32 v1, v35, v118
	v_cvt_pk_bf16_f32 v1, v1, v0
	ds_write_b16 v238, v1 offset:944
	v_mul_f32_e32 v1, v19, v118
	v_cvt_pk_bf16_f32 v1, v1, v0
	ds_write_b16 v238, v1 offset:1008
	v_mul_f32_e32 v1, v68, v119
	v_cvt_pk_bf16_f32 v1, v1, v0
	ds_write_b16 v238, v1 offset:2176
	v_mul_f32_e32 v1, v52, v119
	v_cvt_pk_bf16_f32 v1, v1, v0
	ds_write_b16 v238, v1 offset:2240
	v_mul_f32_e32 v1, v36, v119
	v_cvt_pk_bf16_f32 v1, v1, v0
	ds_write_b16 v238, v1 offset:2304
	v_mul_f32_e32 v1, v20, v119
	v_cvt_pk_bf16_f32 v1, v1, v0
	ds_write_b16 v238, v1 offset:2368
	v_mul_f32_e32 v1, v69, v120
	v_cvt_pk_bf16_f32 v1, v1, v0
	ds_write_b16 v238, v1 offset:2448
	v_mul_f32_e32 v1, v53, v120
	v_cvt_pk_bf16_f32 v1, v1, v0
	ds_write_b16 v238, v1 offset:2512
	v_mul_f32_e32 v1, v37, v120
	v_cvt_pk_bf16_f32 v1, v1, v0
	ds_write_b16 v238, v1 offset:2576
	v_mul_f32_e32 v1, v21, v120
	v_cvt_pk_bf16_f32 v1, v1, v0
	ds_write_b16 v238, v1 offset:2640
	v_mul_f32_e32 v1, v70, v121
	v_cvt_pk_bf16_f32 v1, v1, v0
	ds_write_b16 v238, v1 offset:2720
	v_mul_f32_e32 v1, v54, v121
	v_cvt_pk_bf16_f32 v1, v1, v0
	ds_write_b16 v238, v1 offset:2784
	v_mul_f32_e32 v1, v38, v121
	v_cvt_pk_bf16_f32 v1, v1, v0
	ds_write_b16 v238, v1 offset:2848
	v_mul_f32_e32 v1, v22, v121
	v_cvt_pk_bf16_f32 v1, v1, v0
	ds_write_b16 v238, v1 offset:2912
	v_mul_f32_e32 v1, v71, v122
	v_cvt_pk_bf16_f32 v1, v1, v0
	ds_write_b16 v238, v1 offset:2992
	v_mul_f32_e32 v1, v55, v122
	v_cvt_pk_bf16_f32 v1, v1, v0
	ds_write_b16 v238, v1 offset:3056
	v_mul_f32_e32 v1, v39, v122
	v_cvt_pk_bf16_f32 v1, v1, v0
	ds_write_b16 v238, v1 offset:3120
	v_mul_f32_e32 v1, v23, v122
	v_cvt_pk_bf16_f32 v1, v1, v0
	ds_write_b16 v238, v1 offset:3184
	v_mul_f32_e32 v1, v72, v123
	v_cvt_pk_bf16_f32 v1, v1, v0
	ds_write_b16 v238, v1 offset:4352
	v_mul_f32_e32 v1, v56, v123
	v_cvt_pk_bf16_f32 v1, v1, v0
	ds_write_b16 v238, v1 offset:4416
	v_mul_f32_e32 v1, v40, v123
	v_cvt_pk_bf16_f32 v1, v1, v0
	ds_write_b16 v238, v1 offset:4480
	v_mul_f32_e32 v1, v24, v123
	v_cvt_pk_bf16_f32 v1, v1, v0
	ds_write_b16 v238, v1 offset:4544
	v_mul_f32_e32 v1, v73, v124
	v_cvt_pk_bf16_f32 v1, v1, v0
	ds_write_b16 v238, v1 offset:4624
	v_mul_f32_e32 v1, v57, v124
	v_cvt_pk_bf16_f32 v1, v1, v0
	ds_write_b16 v238, v1 offset:4688
	v_mul_f32_e32 v1, v41, v124
	v_cvt_pk_bf16_f32 v1, v1, v0
	ds_write_b16 v238, v1 offset:4752
	v_mul_f32_e32 v1, v25, v124
	v_cvt_pk_bf16_f32 v1, v1, v0
	ds_write_b16 v238, v1 offset:4816
	v_mul_f32_e32 v1, v74, v125
	v_cvt_pk_bf16_f32 v1, v1, v0
	ds_write_b16 v238, v1 offset:4896
	v_mul_f32_e32 v1, v58, v125
	v_cvt_pk_bf16_f32 v1, v1, v0
	ds_write_b16 v238, v1 offset:4960
	v_mul_f32_e32 v1, v42, v125
; __device__ __forceinline__ unsigned cvt_pk_bf16(float lo, float hi) { unsigned r; asm volatile("v_cvt_pk_bf16_f32 %0, %1, %2" : "=v"(r) : "v"(lo), "v"(hi)); return r; }
; __device__ __forceinline__ float bf_lo(unsigned w) { return __uint_as_float(w << 16); }
; __device__ __forceinline__ float bf_hi(unsigned w) { return __uint_as_float(w & 0xffff0000u); }
; __device__ __forceinline__ float silu_f(float x) { return x * __builtin_amdgcn_rcpf(1.0f + __builtin_amdgcn_exp2f(-1.4426950408889634f * x)); }
; __device__ __forceinline__ void body(const unsigned char* Q8b, const unsigned char* K8h, const unsigned char* VT8h, const bf16_t* Gb, bf16_t* Ob, int seq, char* lds, const int wid, ...
;     ...
;   for (int r = 0; r < 16; ++r) {
; #pragma unroll
;     for (int d0 = 0; d0 < 4; ++d0) *(bf16_t*)(st + ((r & 3) + 8 * (r >> 2)) * ST_ROW + d0 * 64) = (bf16_t)cvt_pk_bf16(o[d0][r] * rli[r], 0.f); }
;   asm volatile("s_waitcnt lgkmcnt(0)" ::: "memory");
;   { const char* sr2 = lds + ST_OFF + wid * (QBLK * ST_ROW) + rw * ST_ROW + ch * 16;
; #pragma unroll
;     for (int i = 0; i < 8; ++i) { const u32x4 ov = *(const u32x4*)(sr2 + i * 4 * ST_ROW); const u32x4 g = gv[i];
;       u32x4 w;
;       w.x = cvt_pk_bf16(bf_lo(ov.x) * silu_f(bf_lo(g.x)), bf_hi(ov.x) * silu_f(bf_hi(g.x)));
;       w.y = cvt_pk_bf16(bf_lo(ov.y) * silu_f(bf_lo(g.y)), bf_hi(ov.y) * silu_f(bf_hi(g.y)));
;       w.z = cvt_pk_bf16(bf_lo(ov.z) * silu_f(bf_lo(g.z)), bf_hi(ov.z) * silu_f(bf_hi(g.z)));
;       w.w = cvt_pk_bf16(bf_lo(ov.w) * silu_f(bf_lo(g.w)), bf_hi(ov.w) * silu_f(bf_hi(g.w)));
;       *(u32x4*)(Ow + i * 4 * LDO) = w; } }
	v_cvt_pk_bf16_f32 v1, v1, v0
	ds_write_b16 v238, v1 offset:5024
	v_mul_f32_e32 v1, v26, v125
	v_cvt_pk_bf16_f32 v1, v1, v0
	ds_write_b16 v238, v1 offset:5088
	v_mul_f32_e32 v1, v75, v126
	v_cvt_pk_bf16_f32 v1, v1, v0
	ds_write_b16 v238, v1 offset:5168
	v_mul_f32_e32 v1, v59, v126
	v_cvt_pk_bf16_f32 v1, v1, v0
	ds_write_b16 v238, v1 offset:5232
	v_mul_f32_e32 v1, v43, v126
	v_cvt_pk_bf16_f32 v1, v1, v0
	ds_write_b16 v238, v1 offset:5296
	v_mul_f32_e32 v1, v27, v126
	v_cvt_pk_bf16_f32 v1, v1, v0
	ds_write_b16 v238, v1 offset:5360
	v_mul_f32_e32 v1, v76, v127
	v_cvt_pk_bf16_f32 v1, v1, v0
	ds_write_b16 v238, v1 offset:6528
	v_mul_f32_e32 v1, v60, v127
	v_cvt_pk_bf16_f32 v1, v1, v0
	ds_write_b16 v238, v1 offset:6592
	v_mul_f32_e32 v1, v44, v127
	v_cvt_pk_bf16_f32 v1, v1, v0
	ds_write_b16 v238, v1 offset:6656
	v_mul_f32_e32 v1, v28, v127
	v_cvt_pk_bf16_f32 v1, v1, v0
	ds_write_b16 v238, v1 offset:6720
	v_mul_f32_e32 v1, v77, v144
	v_cvt_pk_bf16_f32 v1, v1, v0
	ds_write_b16 v238, v1 offset:6800
	v_mul_f32_e32 v1, v61, v144
	v_cvt_pk_bf16_f32 v1, v1, v0
	ds_write_b16 v238, v1 offset:6864
	v_mul_f32_e32 v1, v45, v144
	v_cvt_pk_bf16_f32 v1, v1, v0
	ds_write_b16 v238, v1 offset:6928
	v_mul_f32_e32 v1, v29, v144
	v_cvt_pk_bf16_f32 v1, v1, v0
	ds_write_b16 v238, v1 offset:6992
	v_mul_f32_e32 v1, v78, v145
	v_cvt_pk_bf16_f32 v1, v1, v0
	ds_write_b16 v238, v1 offset:7072
	v_mul_f32_e32 v1, v62, v145
	v_cvt_pk_bf16_f32 v1, v1, v0
	ds_write_b16 v238, v1 offset:7136
	v_mul_f32_e32 v1, v46, v145
	v_cvt_pk_bf16_f32 v1, v1, v0
	ds_write_b16 v238, v1 offset:7200
	v_mul_f32_e32 v1, v30, v145
	v_cvt_pk_bf16_f32 v1, v1, v0
	ds_write_b16 v238, v1 offset:7264
	v_mul_f32_e32 v1, v79, v146
	v_cvt_pk_bf16_f32 v1, v1, v0
	ds_write_b16 v238, v1 offset:7344
	v_mul_f32_e32 v1, v63, v146
	v_cvt_pk_bf16_f32 v1, v1, v0
	ds_write_b16 v238, v1 offset:7408
	v_mul_f32_e32 v1, v47, v146
	v_cvt_pk_bf16_f32 v1, v1, v0
	ds_write_b16 v238, v1 offset:7472
	v_mul_f32_e32 v1, v31, v146
	v_cvt_pk_bf16_f32 v1, v1, v0
	ds_write_b16 v238, v1 offset:7536
	s_waitcnt vmcnt(0)
	v_lshlrev_b32_e32 v1, 16, v112
	v_and_b32_e32 v9, 0xffff0000, v112
	v_mul_f32_e32 v8, 0xbfb8aa3b, v1
	v_mul_f32_e32 v14, 0xbfb8aa3b, v9
	v_exp_f32_e32 v8, v8
	v_exp_f32_e32 v14, v14
	s_waitcnt lgkmcnt(0)
	ds_read_b128 v[4:7], v241
	v_add_f32_e32 v8, 1.0, v8
	v_add_f32_e32 v14, 1.0, v14
	v_rcp_f32_e32 v8, v8
	v_rcp_f32_e32 v14, v14
	s_waitcnt lgkmcnt(0)
	v_lshlrev_b32_e32 v15, 16, v4
	v_and_b32_e32 v4, 0xffff0000, v4
	v_mul_f32_e32 v1, v8, v1
	v_mul_f32_e32 v8, v14, v9
	v_mul_f32_e32 v1, v1, v15
	v_mul_f32_e32 v4, v8, v4
	v_cvt_pk_bf16_f32 v4, v1, v4
	v_lshlrev_b32_e32 v1, 16, v113
	v_and_b32_e32 v9, 0xffff0000, v113
	v_mul_f32_e32 v8, 0xbfb8aa3b, v1
	v_mul_f32_e32 v14, 0xbfb8aa3b, v9
	v_exp_f32_e32 v8, v8
	v_exp_f32_e32 v14, v14
	v_lshlrev_b32_e32 v15, 16, v5
	v_and_b32_e32 v5, 0xffff0000, v5
	v_add_f32_e32 v8, 1.0, v8
	v_add_f32_e32 v14, 1.0, v14
	v_rcp_f32_e32 v8, v8
	v_rcp_f32_e32 v14, v14
	v_mul_f32_e32 v1, v8, v1
	v_mul_f32_e32 v8, v14, v9
	v_mul_f32_e32 v1, v1, v15
	v_mul_f32_e32 v5, v8, v5
	v_cvt_pk_bf16_f32 v5, v1, v5
	v_lshlrev_b32_e32 v1, 16, v114
	v_and_b32_e32 v9, 0xffff0000, v114
	v_mul_f32_e32 v8, 0xbfb8aa3b, v1
	v_mul_f32_e32 v14, 0xbfb8aa3b, v9
	v_exp_f32_e32 v8, v8
	v_exp_f32_e32 v14, v14
	v_lshlrev_b32_e32 v15, 16, v6
	v_and_b32_e32 v6, 0xffff0000, v6
	v_add_f32_e32 v8, 1.0, v8
	v_add_f32_e32 v14, 1.0, v14
	v_rcp_f32_e32 v8, v8
	v_rcp_f32_e32 v14, v14
	v_mul_f32_e32 v1, v8, v1
	v_mul_f32_e32 v8, v14, v9
	v_mul_f32_e32 v1, v1, v15
	v_mul_f32_e32 v6, v8, v6
	v_cvt_pk_bf16_f32 v6, v1, v6
	v_lshlrev_b32_e32 v1, 16, v115
	v_and_b32_e32 v9, 0xffff0000, v115
	v_mul_f32_e32 v8, 0xbfb8aa3b, v1
	v_mul_f32_e32 v14, 0xbfb8aa3b, v9
	v_exp_f32_e32 v8, v8
	v_exp_f32_e32 v14, v14
	v_lshlrev_b32_e32 v15, 16, v7
	v_and_b32_e32 v7, 0xffff0000, v7
	v_add_f32_e32 v8, 1.0, v8
	v_add_f32_e32 v14, 1.0, v14
	v_rcp_f32_e32 v8, v8
	v_rcp_f32_e32 v14, v14
	v_mul_f32_e32 v1, v8, v1
	v_mul_f32_e32 v8, v14, v9
	v_mul_f32_e32 v1, v1, v15
	v_mul_f32_e32 v7, v8, v7
	v_cvt_pk_bf16_f32 v7, v1, v7
	v_lshlrev_b32_e32 v1, 16, v108
	v_and_b32_e32 v9, 0xffff0000, v108
	v_mul_f32_e32 v8, 0xbfb8aa3b, v1
	v_mul_f32_e32 v14, 0xbfb8aa3b, v9
	v_exp_f32_e32 v8, v8
	v_exp_f32_e32 v14, v14
	global_store_dwordx4 v[2:3], v[4:7], off
	ds_read_b128 v[4:7], v241 offset:1088
	v_add_f32_e32 v8, 1.0, v8
	v_add_f32_e32 v14, 1.0, v14
	v_rcp_f32_e32 v8, v8
	v_rcp_f32_e32 v14, v14
	s_waitcnt lgkmcnt(0)
	v_lshlrev_b32_e32 v15, 16, v4
	v_and_b32_e32 v4, 0xffff0000, v4
	v_mul_f32_e32 v1, v8, v1
	v_mul_f32_e32 v8, v14, v9
	v_mul_f32_e32 v1, v1, v15
	v_mul_f32_e32 v4, v8, v4
	v_cvt_pk_bf16_f32 v4, v1, v4
	v_lshlrev_b32_e32 v1, 16, v109
	v_and_b32_e32 v9, 0xffff0000, v109
	v_mul_f32_e32 v8, 0xbfb8aa3b, v1
	v_mul_f32_e32 v14, 0xbfb8aa3b, v9
	v_exp_f32_e32 v8, v8
	v_exp_f32_e32 v14, v14
	v_lshlrev_b32_e32 v15, 16, v5
	v_and_b32_e32 v5, 0xffff0000, v5
	v_add_f32_e32 v8, 1.0, v8
	v_add_f32_e32 v14, 1.0, v14
	v_rcp_f32_e32 v8, v8
	v_rcp_f32_e32 v14, v14
	v_mul_f32_e32 v1, v8, v1
	v_mul_f32_e32 v8, v14, v9
	v_mul_f32_e32 v1, v1, v15
	v_mul_f32_e32 v5, v8, v5
	v_cvt_pk_bf16_f32 v5, v1, v5
	v_lshlrev_b32_e32 v1, 16, v110
	v_and_b32_e32 v9, 0xffff0000, v110
	v_mul_f32_e32 v8, 0xbfb8aa3b, v1
	v_mul_f32_e32 v14, 0xbfb8aa3b, v9
	v_exp_f32_e32 v8, v8
	v_exp_f32_e32 v14, v14
	v_lshlrev_b32_e32 v15, 16, v6
	v_and_b32_e32 v6, 0xffff0000, v6
	v_add_f32_e32 v8, 1.0, v8
	v_add_f32_e32 v14, 1.0, v14
	v_rcp_f32_e32 v8, v8
	v_rcp_f32_e32 v14, v14
	v_mul_f32_e32 v1, v8, v1
	v_mul_f32_e32 v8, v14, v9
	v_mul_f32_e32 v1, v1, v15
	v_mul_f32_e32 v6, v8, v6
	v_cvt_pk_bf16_f32 v6, v1, v6
	v_lshlrev_b32_e32 v1, 16, v111
	v_and_b32_e32 v9, 0xffff0000, v111
	v_mul_f32_e32 v8, 0xbfb8aa3b, v1
	v_mul_f32_e32 v14, 0xbfb8aa3b, v9
	v_exp_f32_e32 v8, v8
	v_exp_f32_e32 v14, v14
	v_lshlrev_b32_e32 v15, 16, v7
	v_and_b32_e32 v7, 0xffff0000, v7
	v_add_f32_e32 v8, 1.0, v8
	v_add_f32_e32 v14, 1.0, v14
	v_rcp_f32_e32 v8, v8
	v_rcp_f32_e32 v14, v14
	v_mul_f32_e32 v1, v8, v1
	v_mul_f32_e32 v8, v14, v9
	v_mul_f32_e32 v7, v8, v7
	v_add_co_u32_e32 v8, vcc, s73, v2
	v_mul_f32_e32 v1, v1, v15
	s_nop 0
	v_addc_co_u32_e32 v9, vcc, 0, v3, vcc
	v_cvt_pk_bf16_f32 v7, v1, v7
	global_store_dwordx4 v[8:9], v[4:7], off
	v_lshlrev_b32_e32 v1, 16, v104
	v_and_b32_e32 v9, 0xffff0000, v104
	v_mul_f32_e32 v8, 0xbfb8aa3b, v1
	v_mul_f32_e32 v14, 0xbfb8aa3b, v9
	v_exp_f32_e32 v8, v8
	v_exp_f32_e32 v14, v14
	ds_read_b128 v[4:7], v241 offset:2176
	v_add_f32_e32 v8, 1.0, v8
	v_add_f32_e32 v14, 1.0, v14
	v_rcp_f32_e32 v8, v8
	v_rcp_f32_e32 v14, v14
	s_waitcnt lgkmcnt(0)
; __device__ __forceinline__ unsigned cvt_pk_bf16(float lo, float hi) { unsigned r; asm volatile("v_cvt_pk_bf16_f32 %0, %1, %2" : "=v"(r) : "v"(lo), "v"(hi)); return r; }
; __device__ __forceinline__ float bf_lo(unsigned w) { return __uint_as_float(w << 16); }
; __device__ __forceinline__ float bf_hi(unsigned w) { return __uint_as_float(w & 0xffff0000u); }
; __device__ __forceinline__ float silu_f(float x) { return x * __builtin_amdgcn_rcpf(1.0f + __builtin_amdgcn_exp2f(-1.4426950408889634f * x)); }
; __device__ __forceinline__ void body(const unsigned char* Q8b, const unsigned char* K8h, const unsigned char* VT8h, const bf16_t* Gb, bf16_t* Ob, int seq, char* lds, const int wid, ...
;     ...
;     for (int i = 0; i < 8; ++i) { const u32x4 ov = *(const u32x4*)(sr2 + i * 4 * ST_ROW); const u32x4 g = gv[i];
;       u32x4 w;
;       w.x = cvt_pk_bf16(bf_lo(ov.x) * silu_f(bf_lo(g.x)), bf_hi(ov.x) * silu_f(bf_hi(g.x)));
;       w.y = cvt_pk_bf16(bf_lo(ov.y) * silu_f(bf_lo(g.y)), bf_hi(ov.y) * silu_f(bf_hi(g.y)));
;       w.z = cvt_pk_bf16(bf_lo(ov.z) * silu_f(bf_lo(g.z)), bf_hi(ov.z) * silu_f(bf_hi(g.z)));
;       w.w = cvt_pk_bf16(bf_lo(ov.w) * silu_f(bf_lo(g.w)), bf_hi(ov.w) * silu_f(bf_hi(g.w)));
;       *(u32x4*)(Ow + i * 4 * LDO) = w; } }
	v_lshlrev_b32_e32 v15, 16, v4
	v_and_b32_e32 v4, 0xffff0000, v4
	v_mul_f32_e32 v1, v8, v1
	v_mul_f32_e32 v8, v14, v9
	v_mul_f32_e32 v1, v1, v15
	v_mul_f32_e32 v4, v8, v4
	v_cvt_pk_bf16_f32 v4, v1, v4
	v_lshlrev_b32_e32 v1, 16, v105
	v_and_b32_e32 v9, 0xffff0000, v105
	v_mul_f32_e32 v8, 0xbfb8aa3b, v1
	v_mul_f32_e32 v14, 0xbfb8aa3b, v9
	v_exp_f32_e32 v8, v8
	v_exp_f32_e32 v14, v14
	v_lshlrev_b32_e32 v15, 16, v5
	v_and_b32_e32 v5, 0xffff0000, v5
	v_add_f32_e32 v8, 1.0, v8
	v_add_f32_e32 v14, 1.0, v14
	v_rcp_f32_e32 v8, v8
	v_rcp_f32_e32 v14, v14
	v_mul_f32_e32 v1, v8, v1
	v_mul_f32_e32 v8, v14, v9
	v_mul_f32_e32 v1, v1, v15
	v_mul_f32_e32 v5, v8, v5
	v_cvt_pk_bf16_f32 v5, v1, v5
	v_lshlrev_b32_e32 v1, 16, v106
	v_and_b32_e32 v9, 0xffff0000, v106
	v_mul_f32_e32 v8, 0xbfb8aa3b, v1
	v_mul_f32_e32 v14, 0xbfb8aa3b, v9
	v_exp_f32_e32 v8, v8
	v_exp_f32_e32 v14, v14
	v_lshlrev_b32_e32 v15, 16, v6
	v_and_b32_e32 v6, 0xffff0000, v6
	v_add_f32_e32 v8, 1.0, v8
	v_add_f32_e32 v14, 1.0, v14
	v_rcp_f32_e32 v8, v8
	v_rcp_f32_e32 v14, v14
	v_mul_f32_e32 v1, v8, v1
	v_mul_f32_e32 v8, v14, v9
	v_mul_f32_e32 v1, v1, v15
	v_mul_f32_e32 v6, v8, v6
	v_cvt_pk_bf16_f32 v6, v1, v6
	v_lshlrev_b32_e32 v1, 16, v107
	v_and_b32_e32 v9, 0xffff0000, v107
	v_mul_f32_e32 v8, 0xbfb8aa3b, v1
	v_mul_f32_e32 v14, 0xbfb8aa3b, v9
	v_exp_f32_e32 v8, v8
	v_exp_f32_e32 v14, v14
	v_lshlrev_b32_e32 v15, 16, v7
	v_and_b32_e32 v7, 0xffff0000, v7
	v_add_f32_e32 v8, 1.0, v8
	v_add_f32_e32 v14, 1.0, v14
	v_rcp_f32_e32 v8, v8
	v_rcp_f32_e32 v14, v14
	v_mul_f32_e32 v1, v8, v1
	v_mul_f32_e32 v8, v14, v9
	v_mul_f32_e32 v7, v8, v7
	v_add_co_u32_e32 v8, vcc, s77, v2
	v_mul_f32_e32 v1, v1, v15
	s_nop 0
	v_addc_co_u32_e32 v9, vcc, 0, v3, vcc
	v_cvt_pk_bf16_f32 v7, v1, v7
	global_store_dwordx4 v[8:9], v[4:7], off
	v_lshlrev_b32_e32 v1, 16, v92
	v_and_b32_e32 v9, 0xffff0000, v92
	v_mul_f32_e32 v8, 0xbfb8aa3b, v1
	v_mul_f32_e32 v14, 0xbfb8aa3b, v9
	v_exp_f32_e32 v8, v8
	v_exp_f32_e32 v14, v14
	ds_read_b128 v[4:7], v241 offset:3264
	v_add_f32_e32 v8, 1.0, v8
	v_add_f32_e32 v14, 1.0, v14
	v_rcp_f32_e32 v8, v8
	v_rcp_f32_e32 v14, v14
	s_waitcnt lgkmcnt(0)
	v_lshlrev_b32_e32 v15, 16, v4
	v_and_b32_e32 v4, 0xffff0000, v4
	v_mul_f32_e32 v1, v8, v1
	v_mul_f32_e32 v8, v14, v9
	v_mul_f32_e32 v1, v1, v15
	v_mul_f32_e32 v4, v8, v4
	v_cvt_pk_bf16_f32 v4, v1, v4
	v_lshlrev_b32_e32 v1, 16, v93
	v_and_b32_e32 v9, 0xffff0000, v93
	v_mul_f32_e32 v8, 0xbfb8aa3b, v1
	v_mul_f32_e32 v14, 0xbfb8aa3b, v9
	v_exp_f32_e32 v8, v8
	v_exp_f32_e32 v14, v14
	v_lshlrev_b32_e32 v15, 16, v5
	v_and_b32_e32 v5, 0xffff0000, v5
	v_add_f32_e32 v8, 1.0, v8
	v_add_f32_e32 v14, 1.0, v14
	v_rcp_f32_e32 v8, v8
	v_rcp_f32_e32 v14, v14
	v_mul_f32_e32 v1, v8, v1
	v_mul_f32_e32 v8, v14, v9
	v_mul_f32_e32 v1, v1, v15
	v_mul_f32_e32 v5, v8, v5
	v_cvt_pk_bf16_f32 v5, v1, v5
	v_lshlrev_b32_e32 v1, 16, v94
	v_and_b32_e32 v9, 0xffff0000, v94
	v_mul_f32_e32 v8, 0xbfb8aa3b, v1
	v_mul_f32_e32 v14, 0xbfb8aa3b, v9
	v_exp_f32_e32 v8, v8
	v_exp_f32_e32 v14, v14
	v_lshlrev_b32_e32 v15, 16, v6
	v_and_b32_e32 v6, 0xffff0000, v6
	v_add_f32_e32 v8, 1.0, v8
	v_add_f32_e32 v14, 1.0, v14
	v_rcp_f32_e32 v8, v8
	v_rcp_f32_e32 v14, v14
	v_mul_f32_e32 v1, v8, v1
	v_mul_f32_e32 v8, v14, v9
	v_mul_f32_e32 v1, v1, v15
	v_mul_f32_e32 v6, v8, v6
	v_cvt_pk_bf16_f32 v6, v1, v6
	v_lshlrev_b32_e32 v1, 16, v95
	v_and_b32_e32 v9, 0xffff0000, v95
	v_mul_f32_e32 v8, 0xbfb8aa3b, v1
	v_mul_f32_e32 v14, 0xbfb8aa3b, v9
	v_exp_f32_e32 v8, v8
	v_exp_f32_e32 v14, v14
	v_lshlrev_b32_e32 v15, 16, v7
	v_and_b32_e32 v7, 0xffff0000, v7
	v_add_f32_e32 v8, 1.0, v8
	v_add_f32_e32 v14, 1.0, v14
	v_rcp_f32_e32 v8, v8
	v_rcp_f32_e32 v14, v14
	v_mul_f32_e32 v1, v8, v1
	v_mul_f32_e32 v8, v14, v9
	v_mul_f32_e32 v7, v8, v7
	v_add_co_u32_e32 v8, vcc, s79, v2
	v_mul_f32_e32 v1, v1, v15
	s_nop 0
	v_addc_co_u32_e32 v9, vcc, 0, v3, vcc
	v_cvt_pk_bf16_f32 v7, v1, v7
	global_store_dwordx4 v[8:9], v[4:7], off
	v_lshlrev_b32_e32 v1, 16, v88
	v_and_b32_e32 v9, 0xffff0000, v88
	v_mul_f32_e32 v8, 0xbfb8aa3b, v1
	v_mul_f32_e32 v14, 0xbfb8aa3b, v9
	v_exp_f32_e32 v8, v8
	v_exp_f32_e32 v14, v14
	ds_read_b128 v[4:7], v241 offset:4352
	v_add_f32_e32 v8, 1.0, v8
	v_add_f32_e32 v14, 1.0, v14
	v_rcp_f32_e32 v8, v8
	v_rcp_f32_e32 v14, v14
	s_waitcnt lgkmcnt(0)
	v_lshlrev_b32_e32 v15, 16, v4
	v_and_b32_e32 v4, 0xffff0000, v4
	v_mul_f32_e32 v1, v8, v1
	v_mul_f32_e32 v8, v14, v9
	v_mul_f32_e32 v1, v1, v15
	v_mul_f32_e32 v4, v8, v4
	v_cvt_pk_bf16_f32 v4, v1, v4
	v_lshlrev_b32_e32 v1, 16, v89
	v_and_b32_e32 v9, 0xffff0000, v89
	v_mul_f32_e32 v8, 0xbfb8aa3b, v1
	v_mul_f32_e32 v14, 0xbfb8aa3b, v9
	v_exp_f32_e32 v8, v8
	v_exp_f32_e32 v14, v14
	v_lshlrev_b32_e32 v15, 16, v5
	v_and_b32_e32 v5, 0xffff0000, v5
	v_add_f32_e32 v8, 1.0, v8
	v_add_f32_e32 v14, 1.0, v14
	v_rcp_f32_e32 v8, v8
	v_rcp_f32_e32 v14, v14
	v_mul_f32_e32 v1, v8, v1
	v_mul_f32_e32 v8, v14, v9
	v_mul_f32_e32 v1, v1, v15
	v_mul_f32_e32 v5, v8, v5
	v_cvt_pk_bf16_f32 v5, v1, v5
	v_lshlrev_b32_e32 v1, 16, v90
	v_and_b32_e32 v9, 0xffff0000, v90
	v_mul_f32_e32 v8, 0xbfb8aa3b, v1
	v_mul_f32_e32 v14, 0xbfb8aa3b, v9
	v_exp_f32_e32 v8, v8
	v_exp_f32_e32 v14, v14
	v_lshlrev_b32_e32 v15, 16, v6
	v_and_b32_e32 v6, 0xffff0000, v6
	v_add_f32_e32 v8, 1.0, v8
	v_add_f32_e32 v14, 1.0, v14
	v_rcp_f32_e32 v8, v8
	v_rcp_f32_e32 v14, v14
	v_mul_f32_e32 v1, v8, v1
	v_mul_f32_e32 v8, v14, v9
	v_mul_f32_e32 v1, v1, v15
	v_mul_f32_e32 v6, v8, v6
	v_cvt_pk_bf16_f32 v6, v1, v6
	v_lshlrev_b32_e32 v1, 16, v91
	v_and_b32_e32 v9, 0xffff0000, v91
	v_mul_f32_e32 v8, 0xbfb8aa3b, v1
	v_mul_f32_e32 v14, 0xbfb8aa3b, v9
	v_exp_f32_e32 v8, v8
	v_exp_f32_e32 v14, v14
	v_lshlrev_b32_e32 v15, 16, v7
	v_and_b32_e32 v7, 0xffff0000, v7
	v_add_f32_e32 v8, 1.0, v8
	v_add_f32_e32 v14, 1.0, v14
	v_rcp_f32_e32 v8, v8
	v_rcp_f32_e32 v14, v14
	v_mul_f32_e32 v1, v8, v1
	v_mul_f32_e32 v8, v14, v9
	v_mul_f32_e32 v7, v8, v7
	v_add_co_u32_e32 v8, vcc, s69, v2
	v_mul_f32_e32 v1, v1, v15
	s_nop 0
	v_addc_co_u32_e32 v9, vcc, 0, v3, vcc
	v_cvt_pk_bf16_f32 v7, v1, v7
	global_store_dwordx4 v[8:9], v[4:7], off
	v_lshlrev_b32_e32 v1, 16, v84
	v_and_b32_e32 v9, 0xffff0000, v84
	v_mul_f32_e32 v8, 0xbfb8aa3b, v1
	v_mul_f32_e32 v14, 0xbfb8aa3b, v9
	v_exp_f32_e32 v8, v8
	v_exp_f32_e32 v14, v14
	ds_read_b128 v[4:7], v241 offset:5440
	v_add_f32_e32 v8, 1.0, v8
	v_add_f32_e32 v14, 1.0, v14
	v_rcp_f32_e32 v8, v8
	v_rcp_f32_e32 v14, v14
	s_waitcnt lgkmcnt(0)
; __device__ __forceinline__ unsigned cvt_pk_bf16(float lo, float hi) { unsigned r; asm volatile("v_cvt_pk_bf16_f32 %0, %1, %2" : "=v"(r) : "v"(lo), "v"(hi)); return r; }
; __device__ __forceinline__ float bf_lo(unsigned w) { return __uint_as_float(w << 16); }
; __device__ __forceinline__ float bf_hi(unsigned w) { return __uint_as_float(w & 0xffff0000u); }
; __device__ __forceinline__ float silu_f(float x) { return x * __builtin_amdgcn_rcpf(1.0f + __builtin_amdgcn_exp2f(-1.4426950408889634f * x)); }
; __device__ __forceinline__ void body(const unsigned char* Q8b, const unsigned char* K8h, const unsigned char* VT8h, const bf16_t* Gb, bf16_t* Ob, int seq, char* lds, const int wid, ...
;     ...
;     for (int i = 0; i < 8; ++i) { const u32x4 ov = *(const u32x4*)(sr2 + i * 4 * ST_ROW); const u32x4 g = gv[i];
;       u32x4 w;
;       w.x = cvt_pk_bf16(bf_lo(ov.x) * silu_f(bf_lo(g.x)), bf_hi(ov.x) * silu_f(bf_hi(g.x)));
;       w.y = cvt_pk_bf16(bf_lo(ov.y) * silu_f(bf_lo(g.y)), bf_hi(ov.y) * silu_f(bf_hi(g.y)));
;       w.z = cvt_pk_bf16(bf_lo(ov.z) * silu_f(bf_lo(g.z)), bf_hi(ov.z) * silu_f(bf_hi(g.z)));
;       w.w = cvt_pk_bf16(bf_lo(ov.w) * silu_f(bf_lo(g.w)), bf_hi(ov.w) * silu_f(bf_hi(g.w)));
;       *(u32x4*)(Ow + i * 4 * LDO) = w; } }
; __global__ void __launch_bounds__(512, 2) fwd_megakernel(Params p) {
;     ...
;         for (int i = 0; have; ++i) {
;             int bn = 0, hn = 0, qbn = 0; const bool hn_ok = UNIT(i + 1, bn, hn, qbn);
;             const size_t m0 = (size_t)b * SEQ + (size_t)qb * 256, qo = m0 * DM + h * HD, ko = (size_t)b * SEQ * KVD + (h >> 2) * HD;
;             const size_t m0n = (size_t)bn * SEQ + (size_t)qbn * 256, qon = m0n * DM + hn * HD, kon = (size_t)bn * SEQ * KVD + (hn >> 2) * HD;
;             att8::body(ws + WS_Q + qo, ws + WS_K + ko, ws + WS_V + (size_t)(b * 2 + (h >> 2)) * 128 * 8192, Gb + qo, Hb + qo, SEQ, (char*)lds, wave,
;                        qr, i > 0, hn_ok, ws + WS_Q + qon, ws + WS_K + kon, ws + WS_V + (size_t)(bn * 2 + (hn >> 2)) * 128 * 8192);
;             b = bn; h = hn; qb = qbn; have = hn_ok;
	v_lshlrev_b32_e32 v15, 16, v4
	v_and_b32_e32 v4, 0xffff0000, v4
	v_mul_f32_e32 v1, v8, v1
	v_mul_f32_e32 v8, v14, v9
	v_mul_f32_e32 v1, v1, v15
	v_mul_f32_e32 v4, v8, v4
	v_cvt_pk_bf16_f32 v4, v1, v4
	v_lshlrev_b32_e32 v1, 16, v85
	v_and_b32_e32 v9, 0xffff0000, v85
	v_mul_f32_e32 v8, 0xbfb8aa3b, v1
	v_mul_f32_e32 v14, 0xbfb8aa3b, v9
	v_exp_f32_e32 v8, v8
	v_exp_f32_e32 v14, v14
	v_lshlrev_b32_e32 v15, 16, v5
	v_and_b32_e32 v5, 0xffff0000, v5
	v_add_f32_e32 v8, 1.0, v8
	v_add_f32_e32 v14, 1.0, v14
	v_rcp_f32_e32 v8, v8
	v_rcp_f32_e32 v14, v14
	v_mul_f32_e32 v1, v8, v1
	v_mul_f32_e32 v8, v14, v9
	v_mul_f32_e32 v1, v1, v15
	v_mul_f32_e32 v5, v8, v5
	v_cvt_pk_bf16_f32 v5, v1, v5
	v_lshlrev_b32_e32 v1, 16, v86
	v_and_b32_e32 v9, 0xffff0000, v86
	v_mul_f32_e32 v8, 0xbfb8aa3b, v1
	v_mul_f32_e32 v14, 0xbfb8aa3b, v9
	v_exp_f32_e32 v8, v8
	v_exp_f32_e32 v14, v14
	v_lshlrev_b32_e32 v15, 16, v6
	v_and_b32_e32 v6, 0xffff0000, v6
	v_add_f32_e32 v8, 1.0, v8
	v_add_f32_e32 v14, 1.0, v14
	v_rcp_f32_e32 v8, v8
	v_rcp_f32_e32 v14, v14
	v_mul_f32_e32 v1, v8, v1
	v_mul_f32_e32 v8, v14, v9
	v_mul_f32_e32 v1, v1, v15
	v_mul_f32_e32 v6, v8, v6
	v_cvt_pk_bf16_f32 v6, v1, v6
	v_lshlrev_b32_e32 v1, 16, v87
	v_and_b32_e32 v9, 0xffff0000, v87
	v_mul_f32_e32 v8, 0xbfb8aa3b, v1
	v_mul_f32_e32 v14, 0xbfb8aa3b, v9
	v_exp_f32_e32 v8, v8
	v_exp_f32_e32 v14, v14
	v_lshlrev_b32_e32 v15, 16, v7
	v_and_b32_e32 v7, 0xffff0000, v7
	v_add_f32_e32 v8, 1.0, v8
	v_add_f32_e32 v14, 1.0, v14
	v_rcp_f32_e32 v8, v8
	v_rcp_f32_e32 v14, v14
	v_mul_f32_e32 v1, v8, v1
	v_mul_f32_e32 v8, v14, v9
	v_mul_f32_e32 v7, v8, v7
	v_add_co_u32_e32 v8, vcc, s71, v2
	v_mul_f32_e32 v1, v1, v15
	s_nop 0
	v_addc_co_u32_e32 v9, vcc, 0, v3, vcc
	v_cvt_pk_bf16_f32 v7, v1, v7
	global_store_dwordx4 v[8:9], v[4:7], off
	v_lshlrev_b32_e32 v1, 16, v80
	v_and_b32_e32 v9, 0xffff0000, v80
	v_mul_f32_e32 v8, 0xbfb8aa3b, v1
	v_mul_f32_e32 v14, 0xbfb8aa3b, v9
	v_exp_f32_e32 v8, v8
	v_exp_f32_e32 v14, v14
	ds_read_b128 v[4:7], v241 offset:6528
	v_add_f32_e32 v8, 1.0, v8
	v_add_f32_e32 v14, 1.0, v14
	v_rcp_f32_e32 v8, v8
	v_rcp_f32_e32 v14, v14
	s_waitcnt lgkmcnt(0)
	v_lshlrev_b32_e32 v15, 16, v4
	v_and_b32_e32 v4, 0xffff0000, v4
	v_mul_f32_e32 v1, v8, v1
	v_mul_f32_e32 v8, v14, v9
	v_mul_f32_e32 v1, v1, v15
	v_mul_f32_e32 v4, v8, v4
	v_cvt_pk_bf16_f32 v4, v1, v4
	v_lshlrev_b32_e32 v1, 16, v81
	v_and_b32_e32 v9, 0xffff0000, v81
	v_mul_f32_e32 v8, 0xbfb8aa3b, v1
	v_mul_f32_e32 v14, 0xbfb8aa3b, v9
	v_exp_f32_e32 v8, v8
	v_exp_f32_e32 v14, v14
	v_lshlrev_b32_e32 v15, 16, v5
	v_and_b32_e32 v5, 0xffff0000, v5
	v_add_f32_e32 v8, 1.0, v8
	v_add_f32_e32 v14, 1.0, v14
	v_rcp_f32_e32 v8, v8
	v_rcp_f32_e32 v14, v14
	v_mul_f32_e32 v1, v8, v1
	v_mul_f32_e32 v8, v14, v9
	v_mul_f32_e32 v1, v1, v15
	v_mul_f32_e32 v5, v8, v5
	v_cvt_pk_bf16_f32 v5, v1, v5
	v_lshlrev_b32_e32 v1, 16, v82
	v_and_b32_e32 v9, 0xffff0000, v82
	v_mul_f32_e32 v8, 0xbfb8aa3b, v1
	v_mul_f32_e32 v14, 0xbfb8aa3b, v9
	v_exp_f32_e32 v8, v8
	v_exp_f32_e32 v14, v14
	v_lshlrev_b32_e32 v15, 16, v6
	v_and_b32_e32 v6, 0xffff0000, v6
	v_add_f32_e32 v8, 1.0, v8
	v_add_f32_e32 v14, 1.0, v14
	v_rcp_f32_e32 v8, v8
	v_rcp_f32_e32 v14, v14
	v_mul_f32_e32 v1, v8, v1
	v_mul_f32_e32 v8, v14, v9
	v_mul_f32_e32 v1, v1, v15
	v_mul_f32_e32 v6, v8, v6
	v_cvt_pk_bf16_f32 v6, v1, v6
	v_lshlrev_b32_e32 v1, 16, v83
	v_and_b32_e32 v9, 0xffff0000, v83
	v_mul_f32_e32 v8, 0xbfb8aa3b, v1
	v_mul_f32_e32 v14, 0xbfb8aa3b, v9
	v_exp_f32_e32 v8, v8
	v_exp_f32_e32 v14, v14
	v_lshlrev_b32_e32 v15, 16, v7
	v_and_b32_e32 v7, 0xffff0000, v7
	v_add_f32_e32 v8, 1.0, v8
	v_add_f32_e32 v14, 1.0, v14
	v_rcp_f32_e32 v8, v8
	v_rcp_f32_e32 v14, v14
	v_mul_f32_e32 v1, v8, v1
	v_mul_f32_e32 v8, v14, v9
	v_mul_f32_e32 v7, v8, v7
	v_add_co_u32_e32 v8, vcc, s75, v2
	v_mul_f32_e32 v1, v1, v15
	s_nop 0
	v_addc_co_u32_e32 v9, vcc, 0, v3, vcc
	v_cvt_pk_bf16_f32 v7, v1, v7
	global_store_dwordx4 v[8:9], v[4:7], off
	v_lshlrev_b32_e32 v1, 16, v10
	v_and_b32_e32 v9, 0xffff0000, v10
	v_mul_f32_e32 v8, 0xbfb8aa3b, v1
	v_mul_f32_e32 v10, 0xbfb8aa3b, v9
	v_exp_f32_e32 v8, v8
	v_exp_f32_e32 v10, v10
	ds_read_b128 v[4:7], v241 offset:7616
	v_add_co_u32_e32 v2, vcc, 0xe000, v2
	v_add_f32_e32 v8, 1.0, v8
	v_add_f32_e32 v10, 1.0, v10
	v_rcp_f32_e32 v8, v8
	v_rcp_f32_e32 v10, v10
	s_waitcnt lgkmcnt(0)
	v_lshlrev_b32_e32 v14, 16, v4
	v_and_b32_e32 v4, 0xffff0000, v4
	v_mul_f32_e32 v1, v8, v1
	v_mul_f32_e32 v8, v10, v9
	v_mul_f32_e32 v1, v1, v14
	v_mul_f32_e32 v4, v8, v4
	v_cvt_pk_bf16_f32 v4, v1, v4
	v_lshlrev_b32_e32 v1, 16, v11
	v_and_b32_e32 v9, 0xffff0000, v11
	v_mul_f32_e32 v8, 0xbfb8aa3b, v1
	v_mul_f32_e32 v10, 0xbfb8aa3b, v9
	v_exp_f32_e32 v8, v8
	v_exp_f32_e32 v10, v10
	v_lshlrev_b32_e32 v11, 16, v5
	v_and_b32_e32 v5, 0xffff0000, v5
	v_add_f32_e32 v8, 1.0, v8
	v_add_f32_e32 v10, 1.0, v10
	v_rcp_f32_e32 v8, v8
	v_rcp_f32_e32 v10, v10
	v_addc_co_u32_e32 v3, vcc, 0, v3, vcc
	v_mul_f32_e32 v1, v8, v1
	v_mul_f32_e32 v8, v10, v9
	v_mul_f32_e32 v1, v1, v11
	v_mul_f32_e32 v5, v8, v5
	v_cvt_pk_bf16_f32 v5, v1, v5
	v_lshlrev_b32_e32 v1, 16, v12
	v_and_b32_e32 v9, 0xffff0000, v12
	v_mul_f32_e32 v8, 0xbfb8aa3b, v1
	v_mul_f32_e32 v10, 0xbfb8aa3b, v9
	v_exp_f32_e32 v8, v8
	v_exp_f32_e32 v10, v10
	v_lshlrev_b32_e32 v11, 16, v6
	v_and_b32_e32 v6, 0xffff0000, v6
	v_add_f32_e32 v8, 1.0, v8
	v_add_f32_e32 v10, 1.0, v10
	v_rcp_f32_e32 v8, v8
	v_rcp_f32_e32 v10, v10
	s_andn2_b64 vcc, exec, s[48:49]
	v_mul_f32_e32 v1, v8, v1
	v_mul_f32_e32 v8, v10, v9
	v_mul_f32_e32 v1, v1, v11
	v_mul_f32_e32 v6, v8, v6
	v_cvt_pk_bf16_f32 v6, v1, v6
	v_lshlrev_b32_e32 v1, 16, v13
	v_and_b32_e32 v9, 0xffff0000, v13
	v_mul_f32_e32 v8, 0xbfb8aa3b, v1
	v_mul_f32_e32 v10, 0xbfb8aa3b, v9
	v_exp_f32_e32 v8, v8
	v_exp_f32_e32 v10, v10
	v_lshlrev_b32_e32 v11, 16, v7
	v_and_b32_e32 v7, 0xffff0000, v7
	v_add_f32_e32 v8, 1.0, v8
	v_add_f32_e32 v10, 1.0, v10
	v_rcp_f32_e32 v8, v8
	v_rcp_f32_e32 v10, v10
	v_mul_f32_e32 v1, v8, v1
	v_mul_f32_e32 v8, v10, v9
	v_mul_f32_e32 v7, v8, v7
	v_mul_f32_e32 v1, v1, v11
	v_cvt_pk_bf16_f32 v7, v1, v7
	global_store_dwordx4 v[2:3], v[4:7], off
	s_cbranch_vccz .LBB0_393

; #define DMA(slot, t) do { \
;     __builtin_amdgcn_global_load_lds((const unsigned*)(Kg + (long)(t) * (64 * 256)), (LAS unsigned*)(L3 + K_OFF + (slot) * SHM_T + wid * 1024), 16, 0, 0); \
;     __builtin_amdgcn_global_load_lds((const unsigned*)(Vg + (long)(t) * 8192), (LAS unsigned*)(L3 + (slot) * SHM_T + wid * 1024), 16, 0, 0); } while (0)
; #define BAR() do { asm volatile("s_waitcnt lgkmcnt(0)" ::: "memory"); __builtin_amdgcn_s_barrier(); asm volatile("" ::: "memory"); } while (0)
; #define WAITV(n) asm volatile("s_waitcnt vmcnt(" #n ")" ::: "memory")
; #define QKT(P0, P1, b) qkt(P0, P1, nm, K_lds + (b) * SHM_T, qr, ko, c00, c01, c10, c11)
; __device__ __forceinline__ void partialSM_first(f32x16& p0, f32x16& p1, f32x16& nm) {
;   const float delta = max32(p0, p1) - PSHIFT;
;   for (int r = 0; r < 16; ++r) { p0[r] -= delta; p1[r] -= delta; nm[r] -= delta; }
;   for (int r = 0; r < 16; ++r) p0[r] = __builtin_amdgcn_exp2f(p0[r]);
; }
; __device__ __forceinline__ void finishSM(f32x16& p0, f32x16& p1, v8i& pf) {
;   for (int r = 0; r < 16; ++r) p1[r] = __builtin_amdgcn_exp2f(p1[r]);
; __device__ __forceinline__ void body(const unsigned char* Q8b, const unsigned char* K8h, const unsigned char* VT8h, const bf16_t* Gb, bf16_t* Ob, int seq, char* lds, const int wid, ...
;     ...
;   if (!pre) { DMA(0, 0); DMA(1, 1); } else BAR();
;   DMA(2, 2);
;   WAITV(2); BAR();
;   QKT(pA0, pA1, 0); partialSM_first(pA0, pA1, nm);
.LBB0_371:
	s_mov_b32 m0, s76
	v_lshl_add_u64 v[2:3], v[220:221], 0, s[42:43]
	global_load_lds_dwordx4 v[2:3], off
	v_lshl_add_u64 v[2:3], v[222:223], 0, s[38:39]
	s_mov_b32 m0, s78
	s_nop 0
	global_load_lds_dwordx4 v[2:3], off
	s_waitcnt vmcnt(2)
	s_waitcnt lgkmcnt(0)
	s_barrier
	ds_read_b128 v[22:25], v243 offset:32768
	ds_read_b128 v[18:21], v242 offset:32768
	ds_read_b128 v[34:37], v242 offset:36864
	ds_read_b128 v[38:41], v243 offset:36864
	v_mov_b64_e32 v[2:3], s[8:9]
	v_mov_b64_e32 v[4:5], s[10:11]
	v_mov_b64_e32 v[6:7], s[12:13]
	v_mov_b64_e32 v[8:9], s[14:15]
	v_mov_b64_e32 v[10:11], s[16:17]
	v_mov_b64_e32 v[12:13], s[18:19]
	v_mov_b64_e32 v[14:15], s[20:21]
	v_mov_b64_e32 v[16:17], s[22:23]
	s_nop 1
	s_waitcnt vmcnt(0) lgkmcnt(0)
	v_mfma_scale_f32_32x32x64_f8f6f4 v[18:33], v[18:25], v[176:183], v[2:17], v240, v239 op_sel_hi:[0,0,0]
	s_xor_b64 s[48:49], s[54:55], -1
	s_add_u32 s56, s56, s36
	s_addc_u32 s57, s57, 0
	v_lshl_add_u64 v[224:225], v[216:217], 0, s[58:59]
	v_lshl_add_u64 v[226:227], v[218:219], 0, s[56:57]
	s_mov_b32 s45, 0
	s_mov_b32 s47, 0
	v_mfma_scale_f32_32x32x64_f8f6f4 v[2:17], v[34:41], v[176:183], v[2:17], v240, v239 op_sel_hi:[0,0,0]
	ds_read_b128 v[38:41], v245 offset:32768
	ds_read_b128 v[34:37], v244 offset:32768
	ds_read_b128 v[42:45], v244 offset:36864
	ds_read_b128 v[46:49], v245 offset:36864
	s_waitcnt lgkmcnt(2)
	v_mfma_scale_f32_32x32x64_f8f6f4 v[18:33], v[34:41], v[184:191], v[18:33], v240, v239 op_sel_hi:[0,0,0]
	s_waitcnt lgkmcnt(0)
	v_mfma_scale_f32_32x32x64_f8f6f4 v[2:17], v[42:49], v[184:191], v[2:17], v240, v239 op_sel_hi:[0,0,0]
	s_nop 15
	s_nop 1
	v_max_f32_e32 v1, v19, v19
	v_max_f32_e32 v34, v18, v18
	v_max_f32_e32 v1, v34, v1
	v_max3_f32 v1, v1, v20, v21
	v_max3_f32 v1, v1, v22, v23
	v_max3_f32 v1, v1, v24, v25
	v_max3_f32 v1, v1, v26, v27
	v_max3_f32 v1, v1, v28, v29
	v_max3_f32 v1, v1, v30, v31
	v_max3_f32 v1, v1, v32, v33
	v_max3_f32 v1, v1, v2, v3
	v_max3_f32 v1, v1, v4, v5
	v_max3_f32 v1, v1, v6, v7
	v_max3_f32 v1, v1, v8, v9
	v_max3_f32 v1, v1, v10, v11
	v_max3_f32 v1, v1, v12, v13
	v_max3_f32 v1, v1, v14, v15
	v_max3_f32 v1, v1, v16, v17
	v_mov_b32_e32 v34, v1
	s_nop 1
	v_permlane32_swap_b32_e32 v1, v34
	v_max_f32_e32 v34, v34, v34
	v_max_f32_e32 v1, v1, v1
	v_max_f32_e32 v1, v1, v34
	v_add_f32_e32 v1, 0xc0a00000, v1
	v_sub_f32_e32 v18, v18, v1
	v_sub_f32_e32 v19, v19, v1
	v_sub_f32_e32 v20, v20, v1
	v_sub_f32_e32 v21, v21, v1
	v_sub_f32_e32 v22, v22, v1
	v_sub_f32_e32 v23, v23, v1
	v_sub_f32_e32 v24, v24, v1
	v_sub_f32_e32 v25, v25, v1
	v_sub_f32_e32 v26, v26, v1
	v_sub_f32_e32 v27, v27, v1
	v_sub_f32_e32 v28, v28, v1
	v_sub_f32_e32 v29, v29, v1
	v_sub_f32_e32 v30, v30, v1
	v_sub_f32_e32 v31, v31, v1
	v_sub_f32_e32 v32, v32, v1
	v_sub_f32_e32 v33, v33, v1
	v_exp_f32_e32 v144, v18
	v_exp_f32_e32 v145, v19
	v_exp_f32_e32 v146, v20
	v_exp_f32_e32 v147, v21
	v_exp_f32_e32 v148, v22
	v_exp_f32_e32 v149, v23
	v_exp_f32_e32 v150, v24
	v_exp_f32_e32 v151, v25
	v_exp_f32_e32 v152, v26
	v_exp_f32_e32 v153, v27
	v_exp_f32_e32 v154, v28
	v_exp_f32_e32 v155, v29
	v_exp_f32_e32 v156, v30
	v_exp_f32_e32 v157, v31
	v_exp_f32_e32 v158, v32
	v_exp_f32_e32 v159, v33
	v_sub_f32_e32 v125, v15, v1
	v_sub_f32_e32 v124, v14, v1
	v_mov_b32_e32 v14, v0
	v_mov_b32_e32 v15, v0
	v_sub_f32_e32 v96, 0x40a00000, v1
	v_sub_f32_e32 v127, v17, v1
	v_sub_f32_e32 v126, v16, v1
	v_sub_f32_e32 v123, v13, v1
	v_sub_f32_e32 v122, v12, v1
	v_sub_f32_e32 v121, v11, v1
	v_sub_f32_e32 v120, v10, v1
	v_sub_f32_e32 v119, v9, v1
	v_sub_f32_e32 v118, v8, v1
	v_sub_f32_e32 v117, v7, v1
	v_sub_f32_e32 v116, v6, v1
	v_sub_f32_e32 v115, v5, v1
	v_sub_f32_e32 v114, v4, v1
	v_sub_f32_e32 v113, v3, v1
	v_sub_f32_e32 v112, v2, v1
	v_mov_b32_e32 v1, v0
	v_mov_b32_e32 v2, v0
	v_mov_b32_e32 v3, v0
	v_mov_b32_e32 v4, v0
	v_mov_b32_e32 v5, v0
	v_mov_b32_e32 v6, v0
	v_mov_b32_e32 v7, v0
	v_mov_b32_e32 v8, v0
	v_mov_b32_e32 v9, v0
	v_mov_b32_e32 v10, v0
	v_mov_b32_e32 v11, v0
	v_mov_b32_e32 v12, v0
	v_mov_b32_e32 v13, v0
	v_mov_b64_e32 v[78:79], v[14:15]
	v_mov_b64_e32 v[62:63], v[14:15]
	v_mov_b64_e32 v[46:47], v[14:15]
	v_mov_b64_e32 v[30:31], v[14:15]
	v_mov_b64_e32 v[94:95], v[14:15]
	v_mov_b32_e32 v97, v96
	v_mov_b32_e32 v98, v96
	v_mov_b32_e32 v99, v96
	v_mov_b32_e32 v100, v96
	v_mov_b32_e32 v101, v96
	v_mov_b32_e32 v102, v96
	v_mov_b32_e32 v103, v96
	v_mov_b32_e32 v104, v96
	v_mov_b32_e32 v105, v96
	v_mov_b32_e32 v106, v96
	v_mov_b32_e32 v107, v96
	v_mov_b32_e32 v108, v96
	v_mov_b32_e32 v109, v96
	v_mov_b32_e32 v110, v96
	v_mov_b32_e32 v111, v96
	v_mov_b64_e32 v[76:77], v[12:13]
	v_mov_b64_e32 v[74:75], v[10:11]
	v_mov_b64_e32 v[72:73], v[8:9]
	v_mov_b64_e32 v[70:71], v[6:7]
	v_mov_b64_e32 v[68:69], v[4:5]
	v_mov_b64_e32 v[66:67], v[2:3]
	v_mov_b64_e32 v[64:65], v[0:1]
	v_mov_b64_e32 v[60:61], v[12:13]
	v_mov_b64_e32 v[58:59], v[10:11]
	v_mov_b64_e32 v[56:57], v[8:9]
	v_mov_b64_e32 v[54:55], v[6:7]
	v_mov_b64_e32 v[52:53], v[4:5]
	v_mov_b64_e32 v[50:51], v[2:3]
	v_mov_b64_e32 v[48:49], v[0:1]
	v_mov_b64_e32 v[44:45], v[12:13]
	v_mov_b64_e32 v[42:43], v[10:11]
	v_mov_b64_e32 v[40:41], v[8:9]
	v_mov_b64_e32 v[38:39], v[6:7]
	v_mov_b64_e32 v[36:37], v[4:5]
	v_mov_b64_e32 v[34:35], v[2:3]
	v_mov_b64_e32 v[32:33], v[0:1]
	v_mov_b64_e32 v[28:29], v[12:13]
	v_mov_b64_e32 v[26:27], v[10:11]
	v_mov_b64_e32 v[24:25], v[8:9]
	v_mov_b64_e32 v[22:23], v[6:7]
	v_mov_b64_e32 v[20:21], v[4:5]
	v_mov_b64_e32 v[18:19], v[2:3]
	v_mov_b64_e32 v[16:17], v[0:1]
	v_mov_b64_e32 v[92:93], v[12:13]
	v_mov_b64_e32 v[90:91], v[10:11]
	v_mov_b64_e32 v[88:89], v[8:9]
	v_mov_b64_e32 v[86:87], v[6:7]
	v_mov_b64_e32 v[84:85], v[4:5]
	v_mov_b64_e32 v[82:83], v[2:3]
	v_mov_b64_e32 v[80:81], v[0:1]
	s_branch .LBB0_374

; #define SBAR() __builtin_amdgcn_sched_barrier(0)
; #define MFMA8Q(A, B, C) __builtin_amdgcn_mfma_scale_f32_32x32x64_f8f6f4(A, B, C, 0, 0, 0, SCL1, 0, 0x7C7C7C7C)
; __device__ __forceinline__ v8i ld32(const char* p0, const char* p1) { const u32x4 a = *(const u32x4*)p0, b = *(const u32x4*)p1; return (v8i){(int)a.x, (int)a.y, (int)a.z, (int)a.w, (int)b.x, (int)b.y, (int)b.z, (int)b.w}; }
; #define DMA(slot, t) do { \
;     __builtin_amdgcn_global_load_lds((const unsigned*)(Kg + (long)(t) * (64 * 256)), (LAS unsigned*)(L3 + K_OFF + (slot) * SHM_T + wid * 1024), 16, 0, 0); \
;     __builtin_amdgcn_global_load_lds((const unsigned*)(Vg + (long)(t) * 8192), (LAS unsigned*)(L3 + (slot) * SHM_T + wid * 1024), 16, 0, 0); } while (0)
; #define BAR() do { asm volatile("s_waitcnt lgkmcnt(0)" ::: "memory"); __builtin_amdgcn_s_barrier(); asm volatile("" ::: "memory"); } while (0)
; #define WAITV(n) asm volatile("s_waitcnt vmcnt(" #n ")" ::: "memory")
; #define RESC(a) do { if (__any((a) < 1.f)) { if (hi == 0) al_l[r32] = (a); asm volatile("s_waitcnt lgkmcnt(0)" ::: "memory"); \
;     for (int r = 0; r < 16; ++r) { const float a_ = al_l[crow(r, hi)]; ls[r] *= a_; for (int d = 0; d < 4; ++d) o[d][r] *= a_; } } } while (0)
; __device__ __forceinline__ void qkt(f32x16& p0, f32x16& p1, const f32x16& nm, const char* Ks, const v8i* qr, int ko, int c00, int c01, int c10, int c11) {
;   { const v8i a0 = ld32(Ks + ko + c00, Ks + ko + c01), a1 = ld32(Ks + 4096 + ko + c00, Ks + 4096 + ko + c01);
;     p0 = MFMA8Q(a0, qr[0], nm); p1 = MFMA8Q(a1, qr[0], nm); }
;   { const v8i a0 = ld32(Ks + ko + c10, Ks + ko + c11), a1 = ld32(Ks + 4096 + ko + c10, Ks + 4096 + ko + c11);
;     p0 = MFMA8Q(a0, qr[1], p0); p1 = MFMA8Q(a1, qr[1], p1); }
; }
; __device__ __forceinline__ void body(const unsigned char* Q8b, const unsigned char* K8h, const unsigned char* VT8h, const bf16_t* Gb, bf16_t* Ob, int seq, char* lds, const int wid, ...
;     ...
;   for (int i = 0; i + 2 < NT; i += 2) {
;     SBAR(); QKT(pB0, pB1, (s0 + 1) & 3);
;     finishSM(pA0, pA1, pf); PIPE1(); SBAR();
;     DMA((s0 + 3) & 3, i + 3);
;     SBAR();
;     HALF2(pB0, pB1, alB, s0);
;     WAITV(2);
;     RESC(alB); BAR();
;     SBAR(); QKT(pA0, pA1, (s0 + 2) & 3);
;     finishSM(pB0, pB1, pf); PIPE1(); SBAR();
;     { const int t4 = (i + 4 < NT) ? i + 4 : NT - 1; DMA(s0, t4); }
;     SBAR();
;     HALF2(pA0, pA1, alA, (s0 + 1) & 3);
.Lstg_a2:
	s_add_i32 s45, s45, 2
	v_lshl_add_u64 v[224:225], v[224:225], 0, s[38:39]
	s_cmpk_gt_u32 s45, 0x7d
	v_lshl_add_u64 v[226:227], v[226:227], 0, s[42:43]
	s_cbranch_scc1 .LBB0_385
	s_branch .Lc2_374
.LBB0_374:
	ds_read_b128 v[2:5], v242 offset:40960
	ds_read_b128 v[6:9], v243 offset:40960
	ds_read_b128 v[128:131], v242 offset:45056
	ds_read_b128 v[132:135], v243 offset:45056
	ds_read_b128 v[194:197], v244 offset:40960
	ds_read_b128 v[198:201], v245 offset:40960
	ds_read_b128 v[246:249], v244 offset:45056
	ds_read_b128 v[250:253], v245 offset:45056
	v_exp_f32_e32 v1, v112
	v_exp_f32_e32 v10, v113
	v_exp_f32_e32 v11, v114
	v_exp_f32_e32 v12, v115
	s_waitcnt lgkmcnt(6)
	s_setprio 1
	v_mfma_scale_f32_32x32x64_f8f6f4 v[160:175], v[2:9], v[176:183], v[96:111], v240, v239 op_sel_hi:[0,0,0]
	v_exp_f32_e32 v6, v116
	v_exp_f32_e32 v7, v117
	v_exp_f32_e32 v8, v118
	v_exp_f32_e32 v9, v119
	v_cvt_pk_fp8_f32 v5, v6, v7
	v_cvt_pk_fp8_f32 v3, v1, v10
	v_cvt_pk_fp8_f32 v5, v8, v9 op_sel:[0,0,1]
	s_waitcnt lgkmcnt(4)
	v_mfma_scale_f32_32x32x64_f8f6f4 v[128:143], v[128:135], v[176:183], v[96:111], v240, v239 op_sel_hi:[0,0,0]
	v_exp_f32_e32 v13, v120
	v_exp_f32_e32 v14, v121
	v_exp_f32_e32 v15, v122
	v_exp_f32_e32 v112, v123
	v_cvt_pk_fp8_f32 v2, v144, v145
	v_cvt_pk_fp8_f32 v4, v148, v149
	v_cvt_pk_fp8_f32 v6, v152, v153
	v_cvt_pk_fp8_f32 v7, v13, v14
	v_cvt_pk_fp8_f32 v8, v156, v157
	v_cvt_pk_fp8_f32 v2, v146, v147 op_sel:[0,0,1]
	v_cvt_pk_fp8_f32 v3, v11, v12 op_sel:[0,0,1]
	v_cvt_pk_fp8_f32 v4, v150, v151 op_sel:[0,0,1]
	v_cvt_pk_fp8_f32 v6, v154, v155 op_sel:[0,0,1]
	v_cvt_pk_fp8_f32 v7, v15, v112 op_sel:[0,0,1]
	v_cvt_pk_fp8_f32 v8, v158, v159 op_sel:[0,0,1]
	s_waitcnt lgkmcnt(2)
	v_mfma_scale_f32_32x32x64_f8f6f4 v[160:175], v[194:201], v[184:191], v[160:175], v240, v239 op_sel_hi:[0,0,0]
	v_exp_f32_e32 v113, v124
	v_exp_f32_e32 v114, v125
	v_exp_f32_e32 v1, v126
	v_exp_f32_e32 v10, v127
	v_permlane32_swap_b32_e32 v2, v3
	v_cvt_pk_fp8_f32 v9, v113, v114
	v_permlane32_swap_b32_e32 v4, v5
	v_permlane32_swap_b32_e32 v6, v7
	v_cvt_pk_fp8_f32 v9, v1, v10 op_sel:[0,0,1]
	s_nop 1
	v_permlane32_swap_b32_e32 v8, v9
	s_waitcnt lgkmcnt(0)
	v_mfma_scale_f32_32x32x64_f8f6f4 v[128:143], v[246:253], v[184:191], v[128:143], v240, v239 op_sel_hi:[0,0,0]
	s_setprio 0
	s_add_i32 m0, s68, 0xe000
	s_nop 0
	global_load_lds_dwordx4 v[226:227], off
	s_add_i32 m0, s68, 0x6000
	s_nop 0
	global_load_lds_dwordx4 v[224:225], off
	ds_read_b128 v[194:197], v254
	ds_read_b128 v[148:151], v254 offset:2048
	ds_read_b128 v[198:201], v255
	ds_read_b128 v[152:155], v255 offset:2048
	ds_read_b128 v[120:123], v254 offset:4096
	ds_read_b128 v[112:115], v254 offset:6144
	ds_read_b128 v[124:127], v255 offset:4096
	ds_read_b128 v[116:119], v255 offset:6144
	v_max_f32_e32 v1, v160, v161
	v_max3_f32 v1, v1, v162, v163
	v_max3_f32 v1, v1, v164, v165
	v_max3_f32 v1, v1, v166, v167
	v_max3_f32 v1, v1, v168, v169
	v_max3_f32 v1, v1, v170, v171
	v_max3_f32 v1, v1, v172, v173
	v_max3_f32 v1, v1, v174, v175
	v_max3_f32 v1, v1, v128, v129
	v_max3_f32 v1, v1, v130, v131
	v_max3_f32 v1, v1, v132, v133
	v_max3_f32 v1, v1, v134, v135
	v_max3_f32 v1, v1, v136, v137
	v_max3_f32 v1, v1, v138, v139
	v_max3_f32 v1, v1, v140, v141
	v_max3_f32 v1, v1, v142, v143
	v_cmp_lt_f32_e32 vcc, s80, v1
	s_cbranch_vccnz .LBB0_383

.Lstg_b1:
	s_waitcnt lgkmcnt(5)
	v_mfma_scale_f32_32x32x64_f8f6f4 v[64:79], v[2:9], v[194:201], v[64:79], v240, v240 op_sel_hi:[0,0,0]
	v_exp_f32_e32 v144, v160
	v_exp_f32_e32 v145, v161
	v_exp_f32_e32 v146, v162
	s_waitcnt lgkmcnt(4)
	v_mfma_scale_f32_32x32x64_f8f6f4 v[48:63], v[2:9], v[148:155], v[48:63], v240, v240 op_sel_hi:[0,0,0]
	v_exp_f32_e32 v147, v163
	v_exp_f32_e32 v148, v164
	v_exp_f32_e32 v149, v165
	s_waitcnt lgkmcnt(1)
	v_mfma_scale_f32_32x32x64_f8f6f4 v[32:47], v[2:9], v[120:127], v[32:47], v240, v240 op_sel_hi:[0,0,0]
	v_exp_f32_e32 v150, v166
	v_exp_f32_e32 v151, v167
	v_exp_f32_e32 v152, v168
	s_waitcnt lgkmcnt(0)
	v_mfma_scale_f32_32x32x64_f8f6f4 v[16:31], v[2:9], v[112:119], v[16:31], v240, v240 op_sel_hi:[0,0,0]
	v_exp_f32_e32 v153, v169
	v_exp_f32_e32 v154, v170
	v_exp_f32_e32 v155, v171
	v_mfma_scale_f32_32x32x64_f8f6f4 v[80:95], v[2:9], v[228:235], v[80:95], v240, v240 op_sel_hi:[0,0,0]
	v_exp_f32_e32 v156, v172
	v_exp_f32_e32 v157, v173
	v_exp_f32_e32 v158, v174
	v_exp_f32_e32 v159, v175
	s_waitcnt vmcnt(2)
	s_cmp_eq_u32 s93, 0
	s_cbranch_scc1 .LBB0_379
	s_mov_b32 s93, 0
	s_and_saveexec_b64 s[56:57], s[4:5]
	ds_write_b32 v236, v1 offset:128
	s_or_b64 exec, exec, s[56:57]
	s_waitcnt lgkmcnt(0)
	v_add_u32_e32 v1, s67, v237
	ds_read_b128 v[2:5], v1 offset:224
	ds_read_b128 v[6:9], v1 offset:192
	ds_read_b128 v[10:13], v1 offset:160
	ds_read_b128 v[112:115], v1 offset:128
	s_waitcnt lgkmcnt(0)
	v_pk_mul_f32 v[76:77], v[76:77], v[2:3]
	v_pk_mul_f32 v[72:73], v[72:73], v[6:7]
	v_pk_mul_f32 v[68:69], v[68:69], v[10:11]
	v_pk_mul_f32 v[78:79], v[78:79], v[4:5]
	v_pk_mul_f32 v[74:75], v[74:75], v[8:9]
	v_pk_mul_f32 v[70:71], v[70:71], v[12:13]
	v_pk_mul_f32 v[66:67], v[66:67], v[114:115]
	v_pk_mul_f32 v[64:65], v[64:65], v[112:113]
	v_pk_mul_f32 v[60:61], v[60:61], v[2:3]
	v_pk_mul_f32 v[56:57], v[56:57], v[6:7]
	v_pk_mul_f32 v[52:53], v[52:53], v[10:11]
	v_pk_mul_f32 v[62:63], v[62:63], v[4:5]
	v_pk_mul_f32 v[58:59], v[58:59], v[8:9]
	v_pk_mul_f32 v[54:55], v[54:55], v[12:13]
	v_pk_mul_f32 v[50:51], v[50:51], v[114:115]
	v_pk_mul_f32 v[48:49], v[48:49], v[112:113]
	v_pk_mul_f32 v[44:45], v[44:45], v[2:3]
	v_pk_mul_f32 v[40:41], v[40:41], v[6:7]
	v_pk_mul_f32 v[36:37], v[36:37], v[10:11]
	v_pk_mul_f32 v[46:47], v[46:47], v[4:5]
	v_pk_mul_f32 v[42:43], v[42:43], v[8:9]
	v_pk_mul_f32 v[38:39], v[38:39], v[12:13]
	v_pk_mul_f32 v[34:35], v[34:35], v[114:115]
	v_pk_mul_f32 v[32:33], v[32:33], v[112:113]
	v_pk_mul_f32 v[28:29], v[28:29], v[2:3]
	v_pk_mul_f32 v[24:25], v[24:25], v[6:7]
	v_pk_mul_f32 v[20:21], v[20:21], v[10:11]
	v_pk_mul_f32 v[30:31], v[30:31], v[4:5]
	v_pk_mul_f32 v[26:27], v[26:27], v[8:9]
	v_pk_mul_f32 v[22:23], v[22:23], v[12:13]
	v_pk_mul_f32 v[18:19], v[18:19], v[114:115]
	v_pk_mul_f32 v[16:17], v[16:17], v[112:113]
	v_pk_mul_f32 v[92:93], v[92:93], v[2:3]
	v_pk_mul_f32 v[88:89], v[88:89], v[6:7]
	v_pk_mul_f32 v[84:85], v[84:85], v[10:11]
	v_pk_mul_f32 v[94:95], v[94:95], v[4:5]
	v_pk_mul_f32 v[90:91], v[90:91], v[8:9]
	v_pk_mul_f32 v[86:87], v[86:87], v[12:13]
	v_pk_mul_f32 v[82:83], v[82:83], v[114:115]
	v_pk_mul_f32 v[80:81], v[80:81], v[112:113]

; #define SBAR() __builtin_amdgcn_sched_barrier(0)
; #define MFMA8Q(A, B, C) __builtin_amdgcn_mfma_scale_f32_32x32x64_f8f6f4(A, B, C, 0, 0, 0, SCL1, 0, 0x7C7C7C7C)
; __device__ __forceinline__ v8i ld32(const char* p0, const char* p1) { const u32x4 a = *(const u32x4*)p0, b = *(const u32x4*)p1; return (v8i){(int)a.x, (int)a.y, (int)a.z, (int)a.w, (int)b.x, (int)b.y, (int)b.z, (int)b.w}; }
; #define DMA(slot, t) do { \
;     __builtin_amdgcn_global_load_lds((const unsigned*)(Kg + (long)(t) * (64 * 256)), (LAS unsigned*)(L3 + K_OFF + (slot) * SHM_T + wid * 1024), 16, 0, 0); \
;     __builtin_amdgcn_global_load_lds((const unsigned*)(Vg + (long)(t) * 8192), (LAS unsigned*)(L3 + (slot) * SHM_T + wid * 1024), 16, 0, 0); } while (0)
; #define QKT(P0, P1, b) qkt(P0, P1, nm, K_lds + (b) * SHM_T, qr, ko, c00, c01, c10, c11)
; #define PIPE1() do { SGB(0x100, 8); SGB(0x400, 4); SGB(0x008, 1); SGB(0x400, 4); SGB(0x008, 1); SGB(0x400, 4); SGB(0x008, 1); SGB(0x400, 4); SGB(0x008, 1); } while (0)
; #define HALF2(Y0, Y1, alY, b) do { PVL(b); const float pm_ = max32(Y0, Y1); adjustSM(Y0, Y1, nm, alY, pm_); SBAR(); \
;     PVM(); exp16(Y0); asm volatile("" : "+v"(Y0)); \
;     SGB(0x008, 1); SGB(0x400, 3); SGB(0x008, 1); SGB(0x400, 3); SGB(0x008, 1); SGB(0x400, 3); SGB(0x008, 1); SGB(0x400, 3); SGB(0x008, 1); SGB(0x400, 4); SBAR(); } while (0)
; __device__ __forceinline__ void qkt(f32x16& p0, f32x16& p1, const f32x16& nm, const char* Ks, const v8i* qr, int ko, int c00, int c01, int c10, int c11) {
;   { const v8i a0 = ld32(Ks + ko + c00, Ks + ko + c01), a1 = ld32(Ks + 4096 + ko + c00, Ks + 4096 + ko + c01);
;     p0 = MFMA8Q(a0, qr[0], nm); p1 = MFMA8Q(a1, qr[0], nm); }
;   { const v8i a0 = ld32(Ks + ko + c10, Ks + ko + c11), a1 = ld32(Ks + 4096 + ko + c10, Ks + 4096 + ko + c11);
;     p0 = MFMA8Q(a0, qr[1], p0); p1 = MFMA8Q(a1, qr[1], p1); }
; }
; __device__ __forceinline__ void body(const unsigned char* Q8b, const unsigned char* K8h, const unsigned char* VT8h, const bf16_t* Gb, bf16_t* Ob, int seq, char* lds, const int wid, ...
;     ...
;     SBAR(); QKT(pA0, pA1, (s0 + 2) & 3);
;     finishSM(pB0, pB1, pf); PIPE1(); SBAR();
;     { const int t4 = (i + 4 < NT) ? i + 4 : NT - 1; DMA(s0, t4); }
;     SBAR();
;     HALF2(pA0, pA1, alA, (s0 + 1) & 3);
.Lstg_a1:
	ds_read_b128 v[2:5], v242 offset:49152
	ds_read_b128 v[6:9], v243 offset:49152
	ds_read_b128 v[112:115], v242 offset:53248
	ds_read_b128 v[116:119], v243 offset:53248
	ds_read_b128 v[194:197], v244 offset:49152
	ds_read_b128 v[198:201], v245 offset:49152
	ds_read_b128 v[246:249], v244 offset:53248
	ds_read_b128 v[250:253], v245 offset:53248
	v_exp_f32_e32 v1, v128
	v_exp_f32_e32 v10, v129
	v_exp_f32_e32 v11, v130
	v_exp_f32_e32 v12, v131
	s_waitcnt lgkmcnt(6)
	s_setprio 1
	v_mfma_scale_f32_32x32x64_f8f6f4 v[160:175], v[2:9], v[176:183], v[96:111], v240, v239 op_sel_hi:[0,0,0]
	v_exp_f32_e32 v6, v132
	v_exp_f32_e32 v7, v133
	v_exp_f32_e32 v8, v134
	v_exp_f32_e32 v9, v135
	v_cvt_pk_fp8_f32 v5, v6, v7
	v_cvt_pk_fp8_f32 v2, v144, v145
	v_cvt_pk_fp8_f32 v5, v8, v9 op_sel:[0,0,1]
	s_waitcnt lgkmcnt(4)
	v_mfma_scale_f32_32x32x64_f8f6f4 v[112:127], v[112:119], v[176:183], v[96:111], v240, v239 op_sel_hi:[0,0,0]
	v_exp_f32_e32 v13, v136
	v_exp_f32_e32 v14, v137
	v_exp_f32_e32 v15, v138
	v_exp_f32_e32 v128, v139
	v_cvt_pk_fp8_f32 v3, v1, v10
	v_cvt_pk_fp8_f32 v4, v148, v149
	v_cvt_pk_fp8_f32 v6, v152, v153
	v_cvt_pk_fp8_f32 v7, v13, v14
	v_cvt_pk_fp8_f32 v8, v156, v157
	v_cvt_pk_fp8_f32 v2, v146, v147 op_sel:[0,0,1]
	v_cvt_pk_fp8_f32 v3, v11, v12 op_sel:[0,0,1]
	v_cvt_pk_fp8_f32 v4, v150, v151 op_sel:[0,0,1]
	v_cvt_pk_fp8_f32 v6, v154, v155 op_sel:[0,0,1]
	v_cvt_pk_fp8_f32 v7, v15, v128 op_sel:[0,0,1]
	v_cvt_pk_fp8_f32 v8, v158, v159 op_sel:[0,0,1]
	s_waitcnt lgkmcnt(2)
	v_mfma_scale_f32_32x32x64_f8f6f4 v[160:175], v[194:201], v[184:191], v[160:175], v240, v239 op_sel_hi:[0,0,0]
	v_exp_f32_e32 v129, v140
	v_exp_f32_e32 v130, v141
	v_exp_f32_e32 v131, v142
	v_exp_f32_e32 v132, v143
	v_permlane32_swap_b32_e32 v2, v3
	v_cvt_pk_fp8_f32 v9, v129, v130
	v_permlane32_swap_b32_e32 v4, v5
	v_permlane32_swap_b32_e32 v6, v7
	v_cvt_pk_fp8_f32 v9, v131, v132 op_sel:[0,0,1]
	s_nop 1
	v_permlane32_swap_b32_e32 v8, v9
	s_waitcnt lgkmcnt(0)
	v_mfma_scale_f32_32x32x64_f8f6f4 v[112:127], v[246:253], v[184:191], v[112:127], v240, v239 op_sel_hi:[0,0,0]
	s_setprio 0
	s_min_u32 s36, s45, 0x7b
	s_add_i32 s56, s36, 4
	s_lshl_b32 s36, s56, 14
	s_add_i32 s57, s68, 0x0
	v_lshl_add_u64 v[10:11], v[220:221], 0, s[36:37]
	s_add_i32 m0, s57, 0x8000
	s_lshl_b32 s36, s56, 13
	global_load_lds_dwordx4 v[10:11], off
	v_lshl_add_u64 v[10:11], v[222:223], 0, s[36:37]
	s_mov_b32 m0, s57
	s_nop 0
	global_load_lds_dwordx4 v[10:11], off
	ds_read_b128 v[194:197], v254 offset:8192
	ds_read_b128 v[148:151], v254 offset:10240
	ds_read_b128 v[198:201], v255 offset:8192
	ds_read_b128 v[152:155], v255 offset:10240
	ds_read_b128 v[136:139], v254 offset:12288
	ds_read_b128 v[128:131], v254 offset:14336
	ds_read_b128 v[140:143], v255 offset:12288
	ds_read_b128 v[132:135], v255 offset:14336
	v_max_f32_e32 v1, v160, v161
	v_max3_f32 v1, v1, v162, v163
	v_max3_f32 v1, v1, v164, v165
	v_max3_f32 v1, v1, v166, v167
	v_max3_f32 v1, v1, v168, v169
	v_max3_f32 v1, v1, v170, v171
	v_max3_f32 v1, v1, v172, v173
	v_max3_f32 v1, v1, v174, v175
	v_max3_f32 v1, v1, v112, v113
	v_max3_f32 v1, v1, v114, v115
	v_max3_f32 v1, v1, v116, v117
	v_max3_f32 v1, v1, v118, v119
	v_max3_f32 v1, v1, v120, v121
	v_max3_f32 v1, v1, v122, v123
	v_max3_f32 v1, v1, v124, v125
	v_max3_f32 v1, v1, v126, v127
	v_cmp_lt_f32_e32 vcc, s80, v1
	s_cbranch_vccnz .LBB0_384

; __device__ __forceinline__ float max32(const f32x16& p0, const f32x16& p1) {
;   float m = p0[0]; for (int r = 1; r < 16; ++r) m = fmaxf(m, p0[r]); for (int r = 0; r < 16; ++r) m = fmaxf(m, p1[r]);
;   { auto rr = __builtin_amdgcn_permlane32_swap(__float_as_uint(m), __float_as_uint(m), false, false);
;     m = fmaxf(__uint_as_float(rr[0]), __uint_as_float(rr[1])); }
;   return m;
; }
; __device__ __forceinline__ void adjustSM(f32x16& p0, f32x16& p1, f32x16& nm, float& alpha, const float pmax) {
;   alpha = 1.f;
;   if (__builtin_expect(__any(pmax > PSHIFT + THR2), 0)) {
;     const float delta = (pmax > PSHIFT + THR2) ? (pmax - PSHIFT) : 0.f;
;     alpha = __builtin_amdgcn_exp2f(-delta);
;     for (int r = 0; r < 16; ++r) { p0[r] -= delta; p1[r] -= delta; nm[r] -= delta; }
;   }
; }
.Lstg_b2:
	s_waitcnt lgkmcnt(5)
	v_mfma_scale_f32_32x32x64_f8f6f4 v[64:79], v[2:9], v[194:201], v[64:79], v240, v240 op_sel_hi:[0,0,0]
	v_exp_f32_e32 v144, v160
	v_exp_f32_e32 v145, v161
	v_exp_f32_e32 v146, v162
	s_waitcnt lgkmcnt(4)
	v_mfma_scale_f32_32x32x64_f8f6f4 v[48:63], v[2:9], v[148:155], v[48:63], v240, v240 op_sel_hi:[0,0,0]
	v_exp_f32_e32 v147, v163
	v_exp_f32_e32 v148, v164
	v_exp_f32_e32 v149, v165
	s_waitcnt lgkmcnt(1)
	v_mfma_scale_f32_32x32x64_f8f6f4 v[32:47], v[2:9], v[136:143], v[32:47], v240, v240 op_sel_hi:[0,0,0]
	v_exp_f32_e32 v150, v166
	v_exp_f32_e32 v151, v167
	v_exp_f32_e32 v152, v168
	s_waitcnt lgkmcnt(0)
	v_mfma_scale_f32_32x32x64_f8f6f4 v[16:31], v[2:9], v[128:135], v[16:31], v240, v240 op_sel_hi:[0,0,0]
	v_exp_f32_e32 v153, v169
	v_exp_f32_e32 v154, v170
	v_exp_f32_e32 v155, v171
	v_mfma_scale_f32_32x32x64_f8f6f4 v[80:95], v[2:9], v[228:235], v[80:95], v240, v240 op_sel_hi:[0,0,0]
	v_exp_f32_e32 v156, v172
	v_exp_f32_e32 v157, v173
	v_exp_f32_e32 v158, v174
	v_exp_f32_e32 v159, v175
	s_waitcnt vmcnt(2)
	s_cmp_eq_u32 s93, 0
	s_cbranch_scc1 .LBB0_373
	s_mov_b32 s93, 0
	s_and_saveexec_b64 s[56:57], s[4:5]
	s_cbranch_execz .LBB0_372
	ds_write_b32 v236, v1 offset:128
	s_branch .LBB0_372
.LBB0_383:
	v_mov_b32_e32 v10, v1
	s_nop 1
	v_permlane32_swap_b32_e32 v1, v10
	v_max_f32_e32 v10, v1, v10
	v_cmp_lt_f32_e32 vcc, s80, v10
	s_mov_b32 s93, 1
	v_add_f32_e32 v1, 0xc0a00000, v10
	s_nop 0
	v_cndmask_b32_e32 v10, 0, v1, vcc
	v_exp_f32_e64 v1, -v10
	v_pk_add_f32 v[160:161], v[160:161], v[10:11] op_sel_hi:[1,0] neg_lo:[0,1] neg_hi:[0,1]
	v_pk_add_f32 v[162:163], v[162:163], v[10:11] op_sel_hi:[1,0] neg_lo:[0,1] neg_hi:[0,1]
	v_pk_add_f32 v[164:165], v[164:165], v[10:11] op_sel_hi:[1,0] neg_lo:[0,1] neg_hi:[0,1]
	v_pk_add_f32 v[166:167], v[166:167], v[10:11] op_sel_hi:[1,0] neg_lo:[0,1] neg_hi:[0,1]
	v_pk_add_f32 v[168:169], v[168:169], v[10:11] op_sel_hi:[1,0] neg_lo:[0,1] neg_hi:[0,1]
	v_pk_add_f32 v[170:171], v[170:171], v[10:11] op_sel_hi:[1,0] neg_lo:[0,1] neg_hi:[0,1]
	v_pk_add_f32 v[172:173], v[172:173], v[10:11] op_sel_hi:[1,0] neg_lo:[0,1] neg_hi:[0,1]
	v_pk_add_f32 v[174:175], v[174:175], v[10:11] op_sel_hi:[1,0] neg_lo:[0,1] neg_hi:[0,1]
	v_sub_f32_e32 v143, v143, v10
	v_sub_f32_e32 v142, v142, v10
	v_sub_f32_e32 v141, v141, v10
	v_sub_f32_e32 v140, v140, v10
	v_sub_f32_e32 v139, v139, v10
	v_sub_f32_e32 v138, v138, v10
	v_sub_f32_e32 v137, v137, v10
	v_sub_f32_e32 v136, v136, v10
	v_sub_f32_e32 v135, v135, v10
	v_sub_f32_e32 v134, v134, v10
	v_sub_f32_e32 v133, v133, v10
	v_sub_f32_e32 v132, v132, v10
	v_sub_f32_e32 v131, v131, v10
	v_sub_f32_e32 v130, v130, v10
	v_sub_f32_e32 v129, v129, v10
	v_sub_f32_e32 v128, v128, v10
	v_sub_f32_e32 v111, v111, v10
	v_sub_f32_e32 v110, v110, v10
	v_sub_f32_e32 v109, v109, v10
	v_sub_f32_e32 v108, v108, v10
	v_sub_f32_e32 v107, v107, v10
	v_sub_f32_e32 v106, v106, v10
	v_sub_f32_e32 v105, v105, v10
	v_sub_f32_e32 v104, v104, v10
	v_sub_f32_e32 v103, v103, v10
	v_sub_f32_e32 v102, v102, v10
	v_sub_f32_e32 v101, v101, v10
	v_sub_f32_e32 v100, v100, v10
	v_sub_f32_e32 v99, v99, v10
	v_sub_f32_e32 v98, v98, v10
	v_sub_f32_e32 v97, v97, v10
	v_sub_f32_e32 v96, v96, v10
	s_branch .LBB0_375
.LBB0_384:
	v_mov_b32_e32 v10, v1
	s_nop 1
	v_permlane32_swap_b32_e32 v1, v10
	v_max_f32_e32 v10, v1, v10
	v_cmp_lt_f32_e32 vcc, s80, v10
	s_mov_b32 s93, 1
	v_add_f32_e32 v1, 0xc0a00000, v10
	s_nop 0
	v_cndmask_b32_e32 v10, 0, v1, vcc
	v_exp_f32_e64 v1, -v10
	v_pk_add_f32 v[160:161], v[160:161], v[10:11] op_sel_hi:[1,0] neg_lo:[0,1] neg_hi:[0,1]
	v_pk_add_f32 v[162:163], v[162:163], v[10:11] op_sel_hi:[1,0] neg_lo:[0,1] neg_hi:[0,1]
	v_pk_add_f32 v[164:165], v[164:165], v[10:11] op_sel_hi:[1,0] neg_lo:[0,1] neg_hi:[0,1]
	v_pk_add_f32 v[166:167], v[166:167], v[10:11] op_sel_hi:[1,0] neg_lo:[0,1] neg_hi:[0,1]
	v_pk_add_f32 v[168:169], v[168:169], v[10:11] op_sel_hi:[1,0] neg_lo:[0,1] neg_hi:[0,1]
	v_pk_add_f32 v[170:171], v[170:171], v[10:11] op_sel_hi:[1,0] neg_lo:[0,1] neg_hi:[0,1]
	v_pk_add_f32 v[172:173], v[172:173], v[10:11] op_sel_hi:[1,0] neg_lo:[0,1] neg_hi:[0,1]
	v_pk_add_f32 v[174:175], v[174:175], v[10:11] op_sel_hi:[1,0] neg_lo:[0,1] neg_hi:[0,1]
	v_sub_f32_e32 v127, v127, v10
	v_sub_f32_e32 v126, v126, v10
	v_sub_f32_e32 v125, v125, v10
	v_sub_f32_e32 v124, v124, v10
	v_sub_f32_e32 v123, v123, v10
	v_sub_f32_e32 v122, v122, v10
	v_sub_f32_e32 v121, v121, v10
	v_sub_f32_e32 v120, v120, v10
	v_sub_f32_e32 v119, v119, v10
	v_sub_f32_e32 v118, v118, v10
	v_sub_f32_e32 v117, v117, v10
	v_sub_f32_e32 v116, v116, v10
	v_sub_f32_e32 v115, v115, v10
	v_sub_f32_e32 v114, v114, v10
	v_sub_f32_e32 v113, v113, v10
	v_sub_f32_e32 v112, v112, v10
	v_sub_f32_e32 v111, v111, v10
	v_sub_f32_e32 v110, v110, v10
	v_sub_f32_e32 v109, v109, v10
	v_sub_f32_e32 v108, v108, v10
	v_sub_f32_e32 v107, v107, v10
	v_sub_f32_e32 v106, v106, v10
	v_sub_f32_e32 v105, v105, v10
	v_sub_f32_e32 v104, v104, v10
	v_sub_f32_e32 v103, v103, v10
	v_sub_f32_e32 v102, v102, v10
	v_sub_f32_e32 v101, v101, v10
	v_sub_f32_e32 v100, v100, v10
	v_sub_f32_e32 v99, v99, v10
	v_sub_f32_e32 v98, v98, v10
	v_sub_f32_e32 v97, v97, v10
	v_sub_f32_e32 v96, v96, v10
	s_branch .LBB0_380

; #define SBAR() __builtin_amdgcn_sched_barrier(0)
; #define MFMA8Q(A, B, C) __builtin_amdgcn_mfma_scale_f32_32x32x64_f8f6f4(A, B, C, 0, 0, 0, SCL1, 0, 0x7C7C7C7C)
; __device__ __forceinline__ v8i ld32(const char* p0, const char* p1) { const u32x4 a = *(const u32x4*)p0, b = *(const u32x4*)p1; return (v8i){(int)a.x, (int)a.y, (int)a.z, (int)a.w, (int)b.x, (int)b.y, (int)b.z, (int)b.w}; }
; #define DMA(slot, t) do { \
;     __builtin_amdgcn_global_load_lds((const unsigned*)(Kg + (long)(t) * (64 * 256)), (LAS unsigned*)(L3 + K_OFF + (slot) * SHM_T + wid * 1024), 16, 0, 0); \
;     __builtin_amdgcn_global_load_lds((const unsigned*)(Vg + (long)(t) * 8192), (LAS unsigned*)(L3 + (slot) * SHM_T + wid * 1024), 16, 0, 0); } while (0)
; #define BAR() do { asm volatile("s_waitcnt lgkmcnt(0)" ::: "memory"); __builtin_amdgcn_s_barrier(); asm volatile("" ::: "memory"); } while (0)
; #define WAITV(n) asm volatile("s_waitcnt vmcnt(" #n ")" ::: "memory")
; #define RESC(a) do { if (__any((a) < 1.f)) { if (hi == 0) al_l[r32] = (a); asm volatile("s_waitcnt lgkmcnt(0)" ::: "memory"); \
;     for (int r = 0; r < 16; ++r) { const float a_ = al_l[crow(r, hi)]; ls[r] *= a_; for (int d = 0; d < 4; ++d) o[d][r] *= a_; } } } while (0)
; __device__ __forceinline__ void qkt(f32x16& p0, f32x16& p1, const f32x16& nm, const char* Ks, const v8i* qr, int ko, int c00, int c01, int c10, int c11) {
;   { const v8i a0 = ld32(Ks + ko + c00, Ks + ko + c01), a1 = ld32(Ks + 4096 + ko + c00, Ks + 4096 + ko + c01);
;     p0 = MFMA8Q(a0, qr[0], nm); p1 = MFMA8Q(a1, qr[0], nm); }
;   { const v8i a0 = ld32(Ks + ko + c10, Ks + ko + c11), a1 = ld32(Ks + 4096 + ko + c10, Ks + 4096 + ko + c11);
;     p0 = MFMA8Q(a0, qr[1], p0); p1 = MFMA8Q(a1, qr[1], p1); }
; }
; __device__ __forceinline__ void body(const unsigned char* Q8b, const unsigned char* K8h, const unsigned char* VT8h, const bf16_t* Gb, bf16_t* Ob, int seq, char* lds, const int wid, ...
;     ...
;   for (int i = 0; i + 2 < NT; i += 2) {
;     SBAR(); QKT(pB0, pB1, (s0 + 1) & 3);
;     finishSM(pA0, pA1, pf); PIPE1(); SBAR();
;     DMA((s0 + 3) & 3, i + 3);
;     SBAR();
;     HALF2(pB0, pB1, alB, s0);
;     WAITV(2);
;     RESC(alB); BAR();
;     SBAR(); QKT(pA0, pA1, (s0 + 2) & 3);
;     finishSM(pB0, pB1, pf); PIPE1(); SBAR();
;     { const int t4 = (i + 4 < NT) ? i + 4 : NT - 1; DMA(s0, t4); }
;     SBAR();
;     HALF2(pA0, pA1, alA, (s0 + 1) & 3);
.Lc2_374:
	ds_read_b128 v[2:5], v242 offset:57344
	ds_read_b128 v[6:9], v243 offset:57344
	ds_read_b128 v[128:131], v242 offset:61440
	ds_read_b128 v[132:135], v243 offset:61440
	ds_read_b128 v[194:197], v244 offset:57344
	ds_read_b128 v[198:201], v245 offset:57344
	ds_read_b128 v[246:249], v244 offset:61440
	ds_read_b128 v[250:253], v245 offset:61440
	v_exp_f32_e32 v1, v112
	v_exp_f32_e32 v10, v113
	v_exp_f32_e32 v11, v114
	v_exp_f32_e32 v12, v115
	s_waitcnt lgkmcnt(6)
	s_setprio 1
	v_mfma_scale_f32_32x32x64_f8f6f4 v[160:175], v[2:9], v[176:183], v[96:111], v240, v239 op_sel_hi:[0,0,0]
	v_exp_f32_e32 v6, v116
	v_exp_f32_e32 v7, v117
	v_exp_f32_e32 v8, v118
	v_exp_f32_e32 v9, v119
	v_cvt_pk_fp8_f32 v5, v6, v7
	v_cvt_pk_fp8_f32 v3, v1, v10
	v_cvt_pk_fp8_f32 v5, v8, v9 op_sel:[0,0,1]
	s_waitcnt lgkmcnt(4)
	v_mfma_scale_f32_32x32x64_f8f6f4 v[128:143], v[128:135], v[176:183], v[96:111], v240, v239 op_sel_hi:[0,0,0]
	v_exp_f32_e32 v13, v120
	v_exp_f32_e32 v14, v121
	v_exp_f32_e32 v15, v122
	v_exp_f32_e32 v112, v123
	v_cvt_pk_fp8_f32 v2, v144, v145
	v_cvt_pk_fp8_f32 v4, v148, v149
	v_cvt_pk_fp8_f32 v6, v152, v153
	v_cvt_pk_fp8_f32 v7, v13, v14
	v_cvt_pk_fp8_f32 v8, v156, v157
	v_cvt_pk_fp8_f32 v2, v146, v147 op_sel:[0,0,1]
	v_cvt_pk_fp8_f32 v3, v11, v12 op_sel:[0,0,1]
	v_cvt_pk_fp8_f32 v4, v150, v151 op_sel:[0,0,1]
	v_cvt_pk_fp8_f32 v6, v154, v155 op_sel:[0,0,1]
	v_cvt_pk_fp8_f32 v7, v15, v112 op_sel:[0,0,1]
	v_cvt_pk_fp8_f32 v8, v158, v159 op_sel:[0,0,1]
	s_waitcnt lgkmcnt(2)
	v_mfma_scale_f32_32x32x64_f8f6f4 v[160:175], v[194:201], v[184:191], v[160:175], v240, v239 op_sel_hi:[0,0,0]
	v_exp_f32_e32 v113, v124
	v_exp_f32_e32 v114, v125
	v_exp_f32_e32 v1, v126
	v_exp_f32_e32 v10, v127
	v_permlane32_swap_b32_e32 v2, v3
	v_cvt_pk_fp8_f32 v9, v113, v114
	v_permlane32_swap_b32_e32 v4, v5
	v_permlane32_swap_b32_e32 v6, v7
	v_cvt_pk_fp8_f32 v9, v1, v10 op_sel:[0,0,1]
	s_nop 1
	v_permlane32_swap_b32_e32 v8, v9
	s_waitcnt lgkmcnt(0)
	v_mfma_scale_f32_32x32x64_f8f6f4 v[128:143], v[246:253], v[184:191], v[128:143], v240, v239 op_sel_hi:[0,0,0]
	s_setprio 0
	s_add_i32 m0, s68, 0xa000
	s_nop 0
	global_load_lds_dwordx4 v[226:227], off
	s_add_i32 m0, s68, 0x2000
	s_nop 0
	global_load_lds_dwordx4 v[224:225], off
	ds_read_b128 v[194:197], v254 offset:16384
	ds_read_b128 v[148:151], v254 offset:18432
	ds_read_b128 v[198:201], v255 offset:16384
	ds_read_b128 v[152:155], v255 offset:18432
	ds_read_b128 v[120:123], v254 offset:20480
	ds_read_b128 v[112:115], v254 offset:22528
	ds_read_b128 v[124:127], v255 offset:20480
	ds_read_b128 v[116:119], v255 offset:22528
	v_max_f32_e32 v1, v160, v161
	v_max3_f32 v1, v1, v162, v163
	v_max3_f32 v1, v1, v164, v165
	v_max3_f32 v1, v1, v166, v167
	v_max3_f32 v1, v1, v168, v169
	v_max3_f32 v1, v1, v170, v171
	v_max3_f32 v1, v1, v172, v173
	v_max3_f32 v1, v1, v174, v175
	v_max3_f32 v1, v1, v128, v129
	v_max3_f32 v1, v1, v130, v131
	v_max3_f32 v1, v1, v132, v133
	v_max3_f32 v1, v1, v134, v135
	v_max3_f32 v1, v1, v136, v137
	v_max3_f32 v1, v1, v138, v139
	v_max3_f32 v1, v1, v140, v141
	v_max3_f32 v1, v1, v142, v143
	v_cmp_lt_f32_e32 vcc, s80, v1
	s_cbranch_vccnz .Lc2_383

; #define SBAR() __builtin_amdgcn_sched_barrier(0)
; #define MFMA8Q(A, B, C) __builtin_amdgcn_mfma_scale_f32_32x32x64_f8f6f4(A, B, C, 0, 0, 0, SCL1, 0, 0x7C7C7C7C)
; __device__ __forceinline__ v8i ld32(const char* p0, const char* p1) { const u32x4 a = *(const u32x4*)p0, b = *(const u32x4*)p1; return (v8i){(int)a.x, (int)a.y, (int)a.z, (int)a.w, (int)b.x, (int)b.y, (int)b.z, (int)b.w}; }
; #define DMA(slot, t) do { \
;     __builtin_amdgcn_global_load_lds((const unsigned*)(Kg + (long)(t) * (64 * 256)), (LAS unsigned*)(L3 + K_OFF + (slot) * SHM_T + wid * 1024), 16, 0, 0); \
;     __builtin_amdgcn_global_load_lds((const unsigned*)(Vg + (long)(t) * 8192), (LAS unsigned*)(L3 + (slot) * SHM_T + wid * 1024), 16, 0, 0); } while (0)
; #define QKT(P0, P1, b) qkt(P0, P1, nm, K_lds + (b) * SHM_T, qr, ko, c00, c01, c10, c11)
; #define PIPE1() do { SGB(0x100, 8); SGB(0x400, 4); SGB(0x008, 1); SGB(0x400, 4); SGB(0x008, 1); SGB(0x400, 4); SGB(0x008, 1); SGB(0x400, 4); SGB(0x008, 1); } while (0)
; #define HALF2(Y0, Y1, alY, b) do { PVL(b); const float pm_ = max32(Y0, Y1); adjustSM(Y0, Y1, nm, alY, pm_); SBAR(); \
;     PVM(); exp16(Y0); asm volatile("" : "+v"(Y0)); \
;     SGB(0x008, 1); SGB(0x400, 3); SGB(0x008, 1); SGB(0x400, 3); SGB(0x008, 1); SGB(0x400, 3); SGB(0x008, 1); SGB(0x400, 3); SGB(0x008, 1); SGB(0x400, 4); SBAR(); } while (0)
; __device__ __forceinline__ void qkt(f32x16& p0, f32x16& p1, const f32x16& nm, const char* Ks, const v8i* qr, int ko, int c00, int c01, int c10, int c11) {
;   { const v8i a0 = ld32(Ks + ko + c00, Ks + ko + c01), a1 = ld32(Ks + 4096 + ko + c00, Ks + 4096 + ko + c01);
;     p0 = MFMA8Q(a0, qr[0], nm); p1 = MFMA8Q(a1, qr[0], nm); }
;   { const v8i a0 = ld32(Ks + ko + c10, Ks + ko + c11), a1 = ld32(Ks + 4096 + ko + c10, Ks + 4096 + ko + c11);
;     p0 = MFMA8Q(a0, qr[1], p0); p1 = MFMA8Q(a1, qr[1], p1); }
; }
; __device__ __forceinline__ void body(const unsigned char* Q8b, const unsigned char* K8h, const unsigned char* VT8h, const bf16_t* Gb, bf16_t* Ob, int seq, char* lds, const int wid, ...
;     ...
;     SBAR(); QKT(pA0, pA1, (s0 + 2) & 3);
;     finishSM(pB0, pB1, pf); PIPE1(); SBAR();
;     { const int t4 = (i + 4 < NT) ? i + 4 : NT - 1; DMA(s0, t4); }
;     SBAR();
;     HALF2(pA0, pA1, alA, (s0 + 1) & 3);
.Lc2stg_a1:
	ds_read_b128 v[2:5], v242 offset:32768
	ds_read_b128 v[6:9], v243 offset:32768
	ds_read_b128 v[112:115], v242 offset:36864
	ds_read_b128 v[116:119], v243 offset:36864
	ds_read_b128 v[194:197], v244 offset:32768
	ds_read_b128 v[198:201], v245 offset:32768
	ds_read_b128 v[246:249], v244 offset:36864
	ds_read_b128 v[250:253], v245 offset:36864
	v_exp_f32_e32 v1, v128
	v_exp_f32_e32 v10, v129
	v_exp_f32_e32 v11, v130
	v_exp_f32_e32 v12, v131
	s_waitcnt lgkmcnt(6)
	s_setprio 1
	v_mfma_scale_f32_32x32x64_f8f6f4 v[160:175], v[2:9], v[176:183], v[96:111], v240, v239 op_sel_hi:[0,0,0]
	v_exp_f32_e32 v6, v132
	v_exp_f32_e32 v7, v133
	v_exp_f32_e32 v8, v134
	v_exp_f32_e32 v9, v135
	v_cvt_pk_fp8_f32 v5, v6, v7
	v_cvt_pk_fp8_f32 v2, v144, v145
	v_cvt_pk_fp8_f32 v5, v8, v9 op_sel:[0,0,1]
	s_waitcnt lgkmcnt(4)
	v_mfma_scale_f32_32x32x64_f8f6f4 v[112:127], v[112:119], v[176:183], v[96:111], v240, v239 op_sel_hi:[0,0,0]
	v_exp_f32_e32 v13, v136
	v_exp_f32_e32 v14, v137
	v_exp_f32_e32 v15, v138
	v_exp_f32_e32 v128, v139
	v_cvt_pk_fp8_f32 v3, v1, v10
	v_cvt_pk_fp8_f32 v4, v148, v149
	v_cvt_pk_fp8_f32 v6, v152, v153
	v_cvt_pk_fp8_f32 v7, v13, v14
	v_cvt_pk_fp8_f32 v8, v156, v157
	v_cvt_pk_fp8_f32 v2, v146, v147 op_sel:[0,0,1]
	v_cvt_pk_fp8_f32 v3, v11, v12 op_sel:[0,0,1]
	v_cvt_pk_fp8_f32 v4, v150, v151 op_sel:[0,0,1]
	v_cvt_pk_fp8_f32 v6, v154, v155 op_sel:[0,0,1]
	v_cvt_pk_fp8_f32 v7, v15, v128 op_sel:[0,0,1]
	v_cvt_pk_fp8_f32 v8, v158, v159 op_sel:[0,0,1]
	s_waitcnt lgkmcnt(2)
	v_mfma_scale_f32_32x32x64_f8f6f4 v[160:175], v[194:201], v[184:191], v[160:175], v240, v239 op_sel_hi:[0,0,0]
	v_exp_f32_e32 v129, v140
	v_exp_f32_e32 v130, v141
	v_exp_f32_e32 v131, v142
	v_exp_f32_e32 v132, v143
	v_permlane32_swap_b32_e32 v2, v3
	v_cvt_pk_fp8_f32 v9, v129, v130
	v_permlane32_swap_b32_e32 v4, v5
	v_permlane32_swap_b32_e32 v6, v7
	v_cvt_pk_fp8_f32 v9, v131, v132 op_sel:[0,0,1]
	s_nop 1
	v_permlane32_swap_b32_e32 v8, v9
	s_waitcnt lgkmcnt(0)
	v_mfma_scale_f32_32x32x64_f8f6f4 v[112:127], v[246:253], v[184:191], v[112:127], v240, v239 op_sel_hi:[0,0,0]
	s_setprio 0
	s_min_u32 s36, s45, 0x7b
	s_add_i32 s56, s36, 4
	s_lshl_b32 s36, s56, 14
	s_add_i32 s57, s68, 0x4000
	v_lshl_add_u64 v[10:11], v[220:221], 0, s[36:37]
	s_add_i32 m0, s57, 0x8000
	s_lshl_b32 s36, s56, 13
	global_load_lds_dwordx4 v[10:11], off
	v_lshl_add_u64 v[10:11], v[222:223], 0, s[36:37]
	s_mov_b32 m0, s57
	s_nop 0
	global_load_lds_dwordx4 v[10:11], off
	ds_read_b128 v[194:197], v254 offset:24576
	ds_read_b128 v[148:151], v254 offset:26624
	ds_read_b128 v[198:201], v255 offset:24576
	ds_read_b128 v[152:155], v255 offset:26624
	ds_read_b128 v[136:139], v254 offset:28672
	ds_read_b128 v[128:131], v254 offset:30720
	ds_read_b128 v[140:143], v255 offset:28672
	ds_read_b128 v[132:135], v255 offset:30720
	v_max_f32_e32 v1, v160, v161
	v_max3_f32 v1, v1, v162, v163
	v_max3_f32 v1, v1, v164, v165
	v_max3_f32 v1, v1, v166, v167
	v_max3_f32 v1, v1, v168, v169
	v_max3_f32 v1, v1, v170, v171
	v_max3_f32 v1, v1, v172, v173
	v_max3_f32 v1, v1, v174, v175
	v_max3_f32 v1, v1, v112, v113
	v_max3_f32 v1, v1, v114, v115
	v_max3_f32 v1, v1, v116, v117
	v_max3_f32 v1, v1, v118, v119
	v_max3_f32 v1, v1, v120, v121
	v_max3_f32 v1, v1, v122, v123
	v_max3_f32 v1, v1, v124, v125
	v_max3_f32 v1, v1, v126, v127
	v_cmp_lt_f32_e32 vcc, s80, v1
	s_cbranch_vccnz .Lc2_384

; #define SBAR() __builtin_amdgcn_sched_barrier(0)
; #define RESC(a) do { if (__any((a) < 1.f)) { if (hi == 0) al_l[r32] = (a); asm volatile("s_waitcnt lgkmcnt(0)" ::: "memory"); \
;     for (int r = 0; r < 16; ++r) { const float a_ = al_l[crow(r, hi)]; ls[r] *= a_; for (int d = 0; d < 4; ++d) o[d][r] *= a_; } } } while (0)
; #define QKT(P0, P1, b) qkt(P0, P1, nm, K_lds + (b) * SHM_T, qr, ko, c00, c01, c10, c11)
; #define HALF2(Y0, Y1, alY, b) do { PVL(b); const float pm_ = max32(Y0, Y1); adjustSM(Y0, Y1, nm, alY, pm_); SBAR(); \
;     PVM(); exp16(Y0); asm volatile("" : "+v"(Y0)); \
;     SGB(0x008, 1); SGB(0x400, 3); SGB(0x008, 1); SGB(0x400, 3); SGB(0x008, 1); SGB(0x400, 3); SGB(0x008, 1); SGB(0x400, 3); SGB(0x008, 1); SGB(0x400, 4); SBAR(); } while (0)
; __device__ __forceinline__ void body(const unsigned char* Q8b, const unsigned char* K8h, const unsigned char* VT8h, const bf16_t* Gb, bf16_t* Ob, int seq, char* lds, const int wid, ...
;     ...
;   SBAR(); QKT(pB0, pB1, (s0 + 1) & 3);
;   finishSM(pA0, pA1, pf); SBAR();
;   HALF2(pB0, pB1, alB, s0);
;   RESC(alB);
.LBB0_385:
	ds_read_b128 v[6:9], v243 offset:57344
	ds_read_b128 v[2:5], v242 offset:57344
	ds_read_b128 v[160:163], v242 offset:61440
	ds_read_b128 v[164:167], v243 offset:61440
	ds_read_b128 v[168:171], v244 offset:57344
	ds_read_b128 v[194:197], v244 offset:61440
	ds_read_b128 v[172:175], v245 offset:57344
	ds_read_b128 v[198:201], v245 offset:61440
	s_waitcnt lgkmcnt(0)
	v_mfma_scale_f32_32x32x64_f8f6f4 v[128:143], v[2:9], v[176:183], v[96:111], v240, v239 op_sel_hi:[0,0,0]
	v_exp_f32_e32 v1, v112
	v_exp_f32_e32 v10, v113
	v_mov_b32_e32 v3, v0
	v_exp_f32_e32 v6, v114
	v_exp_f32_e32 v7, v115
	v_exp_f32_e32 v8, v116
	v_exp_f32_e32 v9, v117
	v_cvt_pk_fp8_f32 v3, v1, v10
	v_exp_f32_e32 v13, v120
	v_exp_f32_e32 v14, v121
	v_exp_f32_e32 v113, v124
	v_exp_f32_e32 v114, v125
	v_mov_b32_e32 v5, v0
	v_mov_b32_e32 v2, v0
	v_mov_b32_e32 v4, v0
	v_mfma_scale_f32_32x32x64_f8f6f4 v[96:111], v[160:167], v[176:183], v[96:111], v240, v239 op_sel_hi:[0,0,0]
	v_cvt_pk_fp8_f32 v5, v8, v9
	v_cvt_pk_fp8_f32 v3, v6, v7 op_sel:[0,0,1]
	v_mov_b32_e32 v6, v0
	v_mov_b32_e32 v7, v0
	v_mov_b32_e32 v8, v0
	v_mov_b32_e32 v9, v0
	v_exp_f32_e32 v11, v118
	v_exp_f32_e32 v12, v119
	v_exp_f32_e32 v15, v122
	v_exp_f32_e32 v112, v123
	v_exp_f32_e32 v115, v126
	v_exp_f32_e32 v116, v127
	v_cvt_pk_fp8_f32 v2, v144, v145
	v_cvt_pk_fp8_f32 v4, v148, v149
	v_cvt_pk_fp8_f32 v6, v152, v153
	v_mfma_scale_f32_32x32x64_f8f6f4 v[128:143], v[168:175], v[184:191], v[128:143], v240, v239 op_sel_hi:[0,0,0]
	v_cvt_pk_fp8_f32 v7, v13, v14
	v_cvt_pk_fp8_f32 v8, v156, v157
	v_cvt_pk_fp8_f32 v9, v113, v114
	v_cvt_pk_fp8_f32 v2, v146, v147 op_sel:[0,0,1]
	v_cvt_pk_fp8_f32 v4, v150, v151 op_sel:[0,0,1]
	v_cvt_pk_fp8_f32 v5, v11, v12 op_sel:[0,0,1]
	v_cvt_pk_fp8_f32 v6, v154, v155 op_sel:[0,0,1]
	v_cvt_pk_fp8_f32 v7, v15, v112 op_sel:[0,0,1]
	v_cvt_pk_fp8_f32 v8, v158, v159 op_sel:[0,0,1]
	v_cvt_pk_fp8_f32 v9, v115, v116 op_sel:[0,0,1]
	v_permlane32_swap_b32_e32 v2, v3
	v_permlane32_swap_b32_e32 v4, v5
	v_permlane32_swap_b32_e32 v6, v7
	v_mfma_scale_f32_32x32x64_f8f6f4 v[96:111], v[194:201], v[184:191], v[96:111], v240, v239 op_sel_hi:[0,0,0]
	v_permlane32_swap_b32_e32 v8, v9
	s_nop 4
	v_max_f32_e32 v11, v129, v129
	v_max_f32_e32 v12, v128, v128
	v_max_f32_e32 v11, v12, v11
	v_max3_f32 v11, v11, v130, v131
	v_max3_f32 v11, v11, v132, v133
	v_max3_f32 v11, v11, v134, v135
	v_max3_f32 v11, v11, v136, v137
	v_max3_f32 v11, v11, v138, v139
	v_max3_f32 v11, v11, v140, v141
	v_max3_f32 v11, v11, v142, v143
	s_nop 3
	v_max3_f32 v11, v11, v96, v97
	v_mov_b32_e32 v1, v254
	v_max3_f32 v11, v11, v98, v99
	v_mov_b32_e32 v10, v255
	ds_read_b128 v[160:163], v1 offset:16384
	ds_read_b128 v[152:155], v1 offset:18432
	ds_read_b128 v[164:167], v10 offset:16384
	ds_read_b128 v[156:159], v10 offset:18432
	ds_read_b128 v[118:121], v1 offset:20480
	ds_read_b128 v[144:147], v1 offset:22528
	ds_read_b128 v[122:125], v10 offset:20480
	ds_read_b128 v[148:151], v10 offset:22528
	v_max3_f32 v11, v11, v100, v101
	v_max3_f32 v11, v11, v102, v103
	v_max3_f32 v11, v11, v104, v105
	v_max3_f32 v11, v11, v106, v107
	v_max3_f32 v11, v11, v108, v109
	v_max3_f32 v11, v11, v110, v111
	v_mov_b32_e32 v12, v11
	s_nop 1
	v_permlane32_swap_b32_e32 v11, v12
	v_max_f32_e32 v12, v12, v12
	v_max_f32_e32 v11, v11, v11
	v_max_f32_e32 v12, v11, v12
	v_cmp_lt_f32_e32 vcc, s80, v12
	v_mov_b32_e32 v11, 1.0
	s_cbranch_vccnz .LBB0_392
.LBB0_386:
	s_waitcnt lgkmcnt(0)
	v_mfma_scale_f32_32x32x64_f8f6f4 v[64:79], v[2:9], v[160:167], v[64:79], v240, v240 op_sel_hi:[0,0,0]
	v_exp_f32_e32 v112, v128
	v_exp_f32_e32 v113, v129
	v_exp_f32_e32 v114, v130
	v_mfma_scale_f32_32x32x64_f8f6f4 v[48:63], v[2:9], v[152:159], v[48:63], v240, v240 op_sel_hi:[0,0,0]
	v_exp_f32_e32 v115, v131
	v_exp_f32_e32 v116, v132
	v_exp_f32_e32 v117, v133
	v_mfma_scale_f32_32x32x64_f8f6f4 v[32:47], v[2:9], v[118:125], v[32:47], v240, v240 op_sel_hi:[0,0,0]
	v_exp_f32_e32 v118, v134
	v_exp_f32_e32 v119, v135
	v_exp_f32_e32 v120, v136
	v_mfma_scale_f32_32x32x64_f8f6f4 v[16:31], v[2:9], v[144:151], v[16:31], v240, v240 op_sel_hi:[0,0,0]
	v_exp_f32_e32 v121, v137
	v_exp_f32_e32 v122, v138
	v_exp_f32_e32 v123, v139
	v_mfma_scale_f32_32x32x64_f8f6f4 v[80:95], v[2:9], v[228:235], v[80:95], v240, v240 op_sel_hi:[0,0,0]
	v_exp_f32_e32 v124, v140
	v_exp_f32_e32 v125, v141
	v_exp_f32_e32 v126, v142
	v_exp_f32_e32 v127, v143
	v_cmp_gt_f32_e32 vcc, 1.0, v11
	s_cbranch_vccz .LBB0_390
	s_and_saveexec_b64 s[56:57], s[4:5]
	ds_write_b32 v236, v11 offset:128
	s_or_b64 exec, exec, s[56:57]
	s_waitcnt lgkmcnt(0)
	v_add_u32_e32 v11, s67, v237
	ds_read_b128 v[2:5], v11 offset:224
	ds_read_b128 v[6:9], v11 offset:192
	ds_read_b128 v[12:15], v11 offset:160
	ds_read_b128 v[128:131], v11 offset:128
	s_waitcnt lgkmcnt(0)
	v_pk_mul_f32 v[76:77], v[76:77], v[2:3]
	v_pk_mul_f32 v[72:73], v[72:73], v[6:7]
	v_pk_mul_f32 v[68:69], v[68:69], v[12:13]
	v_pk_mul_f32 v[78:79], v[78:79], v[4:5]
	v_pk_mul_f32 v[74:75], v[74:75], v[8:9]
	v_pk_mul_f32 v[70:71], v[70:71], v[14:15]
	v_pk_mul_f32 v[66:67], v[66:67], v[130:131]
	v_pk_mul_f32 v[64:65], v[64:65], v[128:129]
	v_pk_mul_f32 v[60:61], v[60:61], v[2:3]
	v_pk_mul_f32 v[56:57], v[56:57], v[6:7]
	v_pk_mul_f32 v[52:53], v[52:53], v[12:13]
	v_pk_mul_f32 v[62:63], v[62:63], v[4:5]
	v_pk_mul_f32 v[58:59], v[58:59], v[8:9]
	v_pk_mul_f32 v[54:55], v[54:55], v[14:15]
	v_pk_mul_f32 v[50:51], v[50:51], v[130:131]
	v_pk_mul_f32 v[48:49], v[48:49], v[128:129]
	v_pk_mul_f32 v[44:45], v[44:45], v[2:3]
	v_pk_mul_f32 v[40:41], v[40:41], v[6:7]
	v_pk_mul_f32 v[36:37], v[36:37], v[12:13]
	v_pk_mul_f32 v[46:47], v[46:47], v[4:5]
	v_pk_mul_f32 v[42:43], v[42:43], v[8:9]
	v_pk_mul_f32 v[38:39], v[38:39], v[14:15]
	v_pk_mul_f32 v[34:35], v[34:35], v[130:131]
	v_pk_mul_f32 v[32:33], v[32:33], v[128:129]
	v_pk_mul_f32 v[28:29], v[28:29], v[2:3]
	v_pk_mul_f32 v[24:25], v[24:25], v[6:7]
	v_pk_mul_f32 v[20:21], v[20:21], v[12:13]
	v_pk_mul_f32 v[30:31], v[30:31], v[4:5]
	v_pk_mul_f32 v[26:27], v[26:27], v[8:9]
	v_pk_mul_f32 v[22:23], v[22:23], v[14:15]
	v_pk_mul_f32 v[18:19], v[18:19], v[130:131]
	v_pk_mul_f32 v[16:17], v[16:17], v[128:129]
	v_pk_mul_f32 v[92:93], v[92:93], v[2:3]
	v_pk_mul_f32 v[88:89], v[88:89], v[6:7]
	v_pk_mul_f32 v[84:85], v[84:85], v[12:13]
	v_pk_mul_f32 v[94:95], v[94:95], v[4:5]
	v_pk_mul_f32 v[90:91], v[90:91], v[8:9]
	v_pk_mul_f32 v[86:87], v[86:87], v[14:15]
	v_pk_mul_f32 v[82:83], v[82:83], v[130:131]
	v_pk_mul_f32 v[80:81], v[80:81], v[128:129]

; #define LAS __attribute__((address_space(3)))
; __device__ __forceinline__ unsigned xb_xcc_id() { return (unsigned)__builtin_amdgcn_s_getreg((3 << 11) | 20) & 0xFu; }
; __device__ __forceinline__ void xcd_barrier(unsigned* bar, volatile LAS unsigned* st, const bool leader) {
;     asm volatile("s_waitcnt vmcnt(0)" ::: "memory");
;     __syncthreads();
;     if (leader) {
;         const unsigned x = xb_xcc_id();
;         __builtin_amdgcn_s_waitcnt(0);
;         unsigned nloc = st[0], nx = st[1];
;         if (nloc == 0u) { xcd_barrier_complete(bar, x, nloc, nx); st[0] = nloc; st[1] = nx; }
.LBB0_393:
	s_setprio 0
	s_cmp_gt_i32 s27, 4
	s_cselect_b64 s[4:5], -1, 0
	s_and_b64 s[6:7], s[6:7], s[4:5]
	s_andn2_b64 vcc, exec, s[6:7]
	s_cbranch_vccnz .LBB0_447
	v_mbcnt_lo_u32_b32 v0, -1, 0
	v_mbcnt_hi_u32_b32 v0, -1, v0
	s_waitcnt vmcnt(0)
	s_and_b32 s6, s3, 0xffffffc0
	v_sub_u32_e32 v0, 0, v0
	v_cmp_eq_u32_e32 vcc, s6, v0
	s_waitcnt vmcnt(0) lgkmcnt(0)
	s_barrier
	s_and_saveexec_b64 s[6:7], vcc
	s_cbranch_execz .LBB0_446
	s_add_i32 s11, 0, 0x23f00
	v_mov_b32_e32 v0, s11
	s_load_dwordx2 s[8:9], s[0:1], 0x80
	s_getreg_b32 s10, hwreg(HW_REG_XCC_ID, 0, 4)
	s_waitcnt vmcnt(0) expcnt(0) lgkmcnt(0)
	ds_read_b32 v2, v0
	s_add_i32 s11, 0, 0x23f04
	v_mov_b32_e32 v0, s11
	ds_read_b32 v0, v0
	s_and_b32 s29, s10, 15
	s_waitcnt lgkmcnt(1)
	v_cmp_ne_u32_e32 vcc, 0, v2
	s_cbranch_vccnz .LBB0_410
	s_add_u32 s10, s8, 0x1000
	s_addc_u32 s11, s9, 0
	s_add_u32 s12, s8, 0x1100
	s_addc_u32 s13, s9, 0
	s_add_u32 s14, s8, 0x1200
	s_addc_u32 s15, s9, 0
	s_mul_i32 s31, s25, s62
	s_add_u32 s16, s8, 0x1300
	s_mul_i32 s31, s31, s24
	s_addc_u32 s17, s9, 0
	s_mov_b32 s34, 1
	v_mov_b32_e32 v16, 0
	s_branch .LBB0_398
